# log2(e) folded into the q pre-scale of the in-projection epilogue (q*log2e/16 rounded to bf16 once), removing the 128 per-lane multiplies before exp2 in the score epilogue
# baseline (speedup 1.0000x reference)
; __device__ __forceinline__ float sigmoidf_(float x) { return __builtin_amdgcn_rcpf(1.0f + __builtin_amdgcn_exp2f(-1.44269504089f * x)); }
; __device__ __forceinline__ u32x2 pk4(f32x4 v) { u32x2 r; r.x = pk_bf16(v[0], v[1]); r.y = pk_bf16(v[2], v[3]); return r; }
; __device__ __forceinline__ int pf(int fq) { return (fq >> 1) | ((fq & 1) << 1); }
;     __device__ __forceinline__ void operator()(const f32x4 (&acc)[2][2][4][2], const Unit& u, int wr, int wc, int fr, int fq) const {
;         if (u.kind <= 2) {
;             const int chw = (u.pn & 15) * 64 + wc * 16, ch = chw + pf(fq) * 4;
;             const int rowb = u.pm * 256 + wr * 64 + fr;
;             if (u.kind == 0) {
;     ...
;             } else {
; #pragma unroll
;                 for (int ai = 0; ai < 2; ++ai) {
;                     u32x2 qv[4];
; #pragma unroll
;                     for (int m = 0; m < 4; ++m) {
;                         const f32x4 Qv = acc[ai][0][m][0], Ga = acc[ai][0][m][1], Gb = acc[ai][1][m][0], Gx = acc[ai][1][m][1]; f32x4 o1, o2, o3;
; #pragma unroll
;                         for (int j = 0; j < 4; ++j) { const float sa = sigmoidf_(Ga[j]), sb = sigmoidf_(Gb[j]), sx = sigmoidf_(Gx[j]);
;                             o1[j] = sa * __builtin_amdgcn_rcpf(fmaxf(sb, 1e-30f)); o2[j] = sb * __builtin_amdgcn_rcpf(fmaxf(sx, 1e-30f)); o3[j] = sx; }
;                         qv[m] = pk4(Qv * 0.0625f);
;                         const int c = (u.pn & 3) * 64 + wc * 16;
;                         const size_t ns = native_slot(u.pm, (u.pn & 15) >> 2, wr * 4 + ((c >> 5) & 3), ai, m, c >> 7, (c >> 4) & 1, pf(fq) * 16 + fr);
;                         __builtin_nontemporal_store(pk4(o1), (u32x2*)SGA + ns); __builtin_nontemporal_store(pk4(o2), (u32x2*)SGB + ns); __builtin_nontemporal_store(pk4(o3), (u32x2*)SGX + ns);
;                     }
; #pragma unroll
;                     for (int pr = 0; pr < 2; ++pr) store_pair16(Q + (size_t)(rowb + ai * 128 + pr * 32) * 1024 + chw, qv[2 * pr], qv[2 * pr + 1], fq);
;                 }
.LBB0_269:
	s_cmp_eq_u32 s13, 1
	s_cbranch_scc1 .Lp1e_k1
	s_cmp_eq_u32 s13, 0
	s_cbranch_scc1 .Lp1e_k0h
	s_cmp_eq_u32 s13, 2
	s_cbranch_scc0 .Lp1e_k0
	v_mbcnt_lo_u32_b32 v240, -1, 0
	v_mbcnt_hi_u32_b32 v240, -1, v240
	v_readlane_b32 s4, v255, 19
	s_nop 3
	s_lshr_b32 s4, s4, 6
	s_lshr_b32 s5, s4, 2
	s_and_b32 s30, s4, 3
	v_and_b32_e32 v241, 15, v240
	v_lshrrev_b32_e32 v242, 4, v240
	v_lshrrev_b32_e32 v243, 1, v242
	v_and_b32_e32 v244, 1, v242
	v_lshl_or_b32 v248, v244, 1, v243
	v_lshl_add_u32 v248, v248, 4, v241
	v_lshl_add_u32 v246, v243, 4, v241
	v_lshlrev_b32_e32 v243, 3, v248
	s_lshl_b32 s31, s96, 8
	s_lshl_b32 s64, s5, 6
	s_add_i32 s31, s31, s64
	v_add_u32_e32 v246, s31, v246
	v_mov_b32_e32 v247, 0
	v_lshlrev_b64 v[246:247], 11, v[246:247]
	s_and_b32 s64, s90, 15
	s_lshl_b32 s64, s64, 6
	s_lshl_b32 vcc_lo, s30, 4
	s_add_i32 s64, s64, vcc_lo
	v_lshlrev_b32_e32 v244, 3, v244
	v_add_u32_e32 v244, s64, v244
	v_lshlrev_b32_e32 v244, 1, v244
	v_mov_b32_e32 v245, 0
	v_lshl_add_u64 v[246:247], v[246:247], 0, v[244:245]
	s_lshl_b32 s64, s96, 2
	s_bfe_u32 vcc_lo, s90, 0x20002
	s_add_i32 s64, s64, vcc_lo
	s_lshl_b32 s64, s64, 17
	s_lshl_b32 vcc_lo, s5, 2
	s_and_b32 vcc_hi, s90, 1
	s_lshl_b32 vcc_hi, vcc_hi, 1
	s_add_i32 vcc_lo, vcc_lo, vcc_hi
	s_lshr_b32 vcc_hi, s30, 1
	s_add_i32 vcc_lo, vcc_lo, vcc_hi
	s_lshl_b32 vcc_lo, vcc_lo, 14
	s_add_i32 s64, s64, vcc_lo
	s_bfe_u32 vcc_lo, s90, 0x10001
	s_lshl_b32 vcc_lo, vcc_lo, 1
	s_and_b32 vcc_hi, s30, 1
	s_add_i32 vcc_lo, vcc_lo, vcc_hi
	s_lshl_b32 vcc_lo, vcc_lo, 9
	s_add_i32 s64, s64, vcc_lo
	s_mov_b32 s42, 0xbfb8aa3b
	s_mov_b32 s43, 1.0
	s_add_u32 s98, s18, s64
	s_addc_u32 s99, s19, 0
	s_add_u32 s100, s98, 0x4000000
	s_addc_u32 s101, s99, 0
	s_add_u32 s30, s20, s64
	s_addc_u32 s31, s21, 0
	s_mov_b32 vcc_lo, 0x3db8aa3b
	s_mov_b32 vcc_hi, 0x3db8aa3b
	v_pk_mul_f32 v[128:129], v[124:125], s[42:43] op_sel_hi:[1,0]
	v_pk_mul_f32 v[130:131], v[126:127], s[42:43] op_sel_hi:[1,0]
	v_pk_mul_f32 v[132:133], v[120:121], s[42:43] op_sel_hi:[1,0]
	v_pk_mul_f32 v[134:135], v[122:123], s[42:43] op_sel_hi:[1,0]
	v_pk_mul_f32 v[136:137], v[112:113], s[42:43] op_sel_hi:[1,0]
	v_pk_mul_f32 v[138:139], v[114:115], s[42:43] op_sel_hi:[1,0]
	v_pk_mul_f32 v[116:117], v[116:117], vcc op_sel_hi:[1,0]
	v_pk_mul_f32 v[118:119], v[118:119], vcc op_sel_hi:[1,0]
	v_exp_f32_e32 v128, v128
	v_exp_f32_e32 v129, v129
	v_exp_f32_e32 v130, v130
	v_exp_f32_e32 v131, v131
	v_exp_f32_e32 v132, v132
	v_exp_f32_e32 v133, v133
	v_exp_f32_e32 v134, v134
	v_exp_f32_e32 v135, v135
	v_exp_f32_e32 v136, v136
	v_exp_f32_e32 v137, v137
	v_exp_f32_e32 v138, v138
	v_exp_f32_e32 v139, v139
	v_pk_add_f32 v[128:129], v[128:129], s[42:43] op_sel:[0,1] op_sel_hi:[1,1]
	v_pk_add_f32 v[130:131], v[130:131], s[42:43] op_sel:[0,1] op_sel_hi:[1,1]
	v_pk_add_f32 v[132:133], v[132:133], s[42:43] op_sel:[0,1] op_sel_hi:[1,1]
	v_pk_add_f32 v[134:135], v[134:135], s[42:43] op_sel:[0,1] op_sel_hi:[1,1]
	v_pk_add_f32 v[136:137], v[136:137], s[42:43] op_sel:[0,1] op_sel_hi:[1,1]
	v_pk_add_f32 v[138:139], v[138:139], s[42:43] op_sel:[0,1] op_sel_hi:[1,1]
	v_rcp_f32_e32 v128, v128
	v_rcp_f32_e32 v129, v129
	v_rcp_f32_e32 v130, v130
	v_rcp_f32_e32 v131, v131
	v_rcp_f32_e32 v176, v132
	v_rcp_f32_e32 v177, v133
	v_rcp_f32_e32 v178, v134
	v_rcp_f32_e32 v179, v135
	v_rcp_f32_e32 v180, v136
	v_rcp_f32_e32 v181, v137
	v_rcp_f32_e32 v182, v138
	v_rcp_f32_e32 v183, v139
	v_min_f32_e32 v132, 0x7149f2ca, v132
	v_min_f32_e32 v133, 0x7149f2ca, v133
	v_min_f32_e32 v134, 0x7149f2ca, v134
	v_min_f32_e32 v135, 0x7149f2ca, v135
	v_min_f32_e32 v136, 0x7149f2ca, v136
	v_min_f32_e32 v137, 0x7149f2ca, v137
	v_min_f32_e32 v138, 0x7149f2ca, v138
	v_min_f32_e32 v139, 0x7149f2ca, v139
	v_pk_mul_f32 v[128:129], v[128:129], v[132:133]
	v_pk_mul_f32 v[130:131], v[130:131], v[134:135]
	v_pk_mul_f32 v[176:177], v[176:177], v[136:137]
	v_pk_mul_f32 v[178:179], v[178:179], v[138:139]
	v_cvt_pk_bf16_f32 v198, v116, v117
	v_cvt_pk_bf16_f32 v199, v118, v119
	v_cvt_pk_bf16_f32 v188, v180, v181
	v_cvt_pk_bf16_f32 v189, v182, v183
	v_cvt_pk_bf16_f32 v184, v128, v129
	v_cvt_pk_bf16_f32 v185, v130, v131
	v_cvt_pk_bf16_f32 v186, v176, v177
	v_cvt_pk_bf16_f32 v187, v178, v179
	global_store_dwordx2 v243, v[184:185], s[98:99] nt
	global_store_dwordx2 v243, v[186:187], s[100:101] nt
	global_store_dwordx2 v243, v[188:189], s[30:31] nt
	s_add_u32 s98, s98, 0x800
	s_addc_u32 s99, s99, 0
	s_add_u32 s100, s100, 0x800
	s_addc_u32 s101, s101, 0
	s_add_u32 s30, s30, 0x800
	s_addc_u32 s31, s31, 0
	v_pk_mul_f32 v[128:129], v[108:109], s[42:43] op_sel_hi:[1,0]
	v_pk_mul_f32 v[130:131], v[110:111], s[42:43] op_sel_hi:[1,0]
	v_pk_mul_f32 v[132:133], v[104:105], s[42:43] op_sel_hi:[1,0]
	v_pk_mul_f32 v[134:135], v[106:107], s[42:43] op_sel_hi:[1,0]
	v_pk_mul_f32 v[136:137], v[80:81], s[42:43] op_sel_hi:[1,0]
	v_pk_mul_f32 v[138:139], v[82:83], s[42:43] op_sel_hi:[1,0]
	v_pk_mul_f32 v[84:85], v[84:85], vcc op_sel_hi:[1,0]
	v_pk_mul_f32 v[86:87], v[86:87], vcc op_sel_hi:[1,0]
	v_exp_f32_e32 v128, v128
	v_exp_f32_e32 v129, v129
	v_exp_f32_e32 v130, v130
	v_exp_f32_e32 v131, v131
	v_exp_f32_e32 v132, v132
	v_exp_f32_e32 v133, v133
	v_exp_f32_e32 v134, v134
	v_exp_f32_e32 v135, v135
	v_exp_f32_e32 v136, v136
	v_exp_f32_e32 v137, v137
	v_exp_f32_e32 v138, v138
	v_exp_f32_e32 v139, v139
	v_pk_add_f32 v[128:129], v[128:129], s[42:43] op_sel:[0,1] op_sel_hi:[1,1]
	v_pk_add_f32 v[130:131], v[130:131], s[42:43] op_sel:[0,1] op_sel_hi:[1,1]
	v_pk_add_f32 v[132:133], v[132:133], s[42:43] op_sel:[0,1] op_sel_hi:[1,1]
	v_pk_add_f32 v[134:135], v[134:135], s[42:43] op_sel:[0,1] op_sel_hi:[1,1]
	v_pk_add_f32 v[136:137], v[136:137], s[42:43] op_sel:[0,1] op_sel_hi:[1,1]
; __device__ __forceinline__ float sigmoidf_(float x) { return __builtin_amdgcn_rcpf(1.0f + __builtin_amdgcn_exp2f(-1.44269504089f * x)); }
; __device__ __forceinline__ u32x2 pk4(f32x4 v) { u32x2 r; r.x = pk_bf16(v[0], v[1]); r.y = pk_bf16(v[2], v[3]); return r; }
; __device__ __forceinline__ int pf(int fq) { return (fq >> 1) | ((fq & 1) << 1); }
;     __device__ __forceinline__ void operator()(const f32x4 (&acc)[2][2][4][2], const Unit& u, int wr, int wc, int fr, int fq) const {
;     ...
;                     for (int m = 0; m < 4; ++m) {
;                         const f32x4 Qv = acc[ai][0][m][0], Ga = acc[ai][0][m][1], Gb = acc[ai][1][m][0], Gx = acc[ai][1][m][1]; f32x4 o1, o2, o3;
; #pragma unroll
;                         for (int j = 0; j < 4; ++j) { const float sa = sigmoidf_(Ga[j]), sb = sigmoidf_(Gb[j]), sx = sigmoidf_(Gx[j]);
;                             o1[j] = sa * __builtin_amdgcn_rcpf(fmaxf(sb, 1e-30f)); o2[j] = sb * __builtin_amdgcn_rcpf(fmaxf(sx, 1e-30f)); o3[j] = sx; }
;                         qv[m] = pk4(Qv * 0.0625f);
;                         const int c = (u.pn & 3) * 64 + wc * 16;
;                         const size_t ns = native_slot(u.pm, (u.pn & 15) >> 2, wr * 4 + ((c >> 5) & 3), ai, m, c >> 7, (c >> 4) & 1, pf(fq) * 16 + fr);
;                         __builtin_nontemporal_store(pk4(o1), (u32x2*)SGA + ns); __builtin_nontemporal_store(pk4(o2), (u32x2*)SGB + ns); __builtin_nontemporal_store(pk4(o3), (u32x2*)SGX + ns);
;                     }
	v_pk_add_f32 v[138:139], v[138:139], s[42:43] op_sel:[0,1] op_sel_hi:[1,1]
	v_rcp_f32_e32 v128, v128
	v_rcp_f32_e32 v129, v129
	v_rcp_f32_e32 v130, v130
	v_rcp_f32_e32 v131, v131
	v_rcp_f32_e32 v176, v132
	v_rcp_f32_e32 v177, v133
	v_rcp_f32_e32 v178, v134
	v_rcp_f32_e32 v179, v135
	v_rcp_f32_e32 v180, v136
	v_rcp_f32_e32 v181, v137
	v_rcp_f32_e32 v182, v138
	v_rcp_f32_e32 v183, v139
	v_min_f32_e32 v132, 0x7149f2ca, v132
	v_min_f32_e32 v133, 0x7149f2ca, v133
	v_min_f32_e32 v134, 0x7149f2ca, v134
	v_min_f32_e32 v135, 0x7149f2ca, v135
	v_min_f32_e32 v136, 0x7149f2ca, v136
	v_min_f32_e32 v137, 0x7149f2ca, v137
	v_min_f32_e32 v138, 0x7149f2ca, v138
	v_min_f32_e32 v139, 0x7149f2ca, v139
	v_pk_mul_f32 v[128:129], v[128:129], v[132:133]
	v_pk_mul_f32 v[130:131], v[130:131], v[134:135]
	v_pk_mul_f32 v[176:177], v[176:177], v[136:137]
	v_pk_mul_f32 v[178:179], v[178:179], v[138:139]
	v_cvt_pk_bf16_f32 v200, v84, v85
	v_cvt_pk_bf16_f32 v201, v86, v87
	v_cvt_pk_bf16_f32 v224, v180, v181
	v_cvt_pk_bf16_f32 v225, v182, v183
	v_cvt_pk_bf16_f32 v220, v128, v129
	v_cvt_pk_bf16_f32 v221, v130, v131
	v_cvt_pk_bf16_f32 v222, v176, v177
	v_cvt_pk_bf16_f32 v223, v178, v179
	global_store_dwordx2 v243, v[220:221], s[98:99] nt
	global_store_dwordx2 v243, v[222:223], s[100:101] nt
	global_store_dwordx2 v243, v[224:225], s[30:31] nt
	s_add_u32 s98, s98, 0x800
	s_addc_u32 s99, s99, 0
	s_add_u32 s100, s100, 0x800
	s_addc_u32 s101, s101, 0
	s_add_u32 s30, s30, 0x800
	s_addc_u32 s31, s31, 0
	v_pk_mul_f32 v[128:129], v[100:101], s[42:43] op_sel_hi:[1,0]
	v_pk_mul_f32 v[130:131], v[102:103], s[42:43] op_sel_hi:[1,0]
	v_pk_mul_f32 v[132:133], v[96:97], s[42:43] op_sel_hi:[1,0]
	v_pk_mul_f32 v[134:135], v[98:99], s[42:43] op_sel_hi:[1,0]
	v_pk_mul_f32 v[136:137], v[72:73], s[42:43] op_sel_hi:[1,0]
	v_pk_mul_f32 v[138:139], v[74:75], s[42:43] op_sel_hi:[1,0]
	v_pk_mul_f32 v[76:77], v[76:77], vcc op_sel_hi:[1,0]
	v_pk_mul_f32 v[78:79], v[78:79], vcc op_sel_hi:[1,0]
	v_exp_f32_e32 v128, v128
	v_exp_f32_e32 v129, v129
	v_exp_f32_e32 v130, v130
	v_exp_f32_e32 v131, v131
	v_exp_f32_e32 v132, v132
	v_exp_f32_e32 v133, v133
	v_exp_f32_e32 v134, v134
	v_exp_f32_e32 v135, v135
	v_exp_f32_e32 v136, v136
	v_exp_f32_e32 v137, v137
	v_exp_f32_e32 v138, v138
	v_exp_f32_e32 v139, v139
	v_pk_add_f32 v[128:129], v[128:129], s[42:43] op_sel:[0,1] op_sel_hi:[1,1]
	v_pk_add_f32 v[130:131], v[130:131], s[42:43] op_sel:[0,1] op_sel_hi:[1,1]
	v_pk_add_f32 v[132:133], v[132:133], s[42:43] op_sel:[0,1] op_sel_hi:[1,1]
	v_pk_add_f32 v[134:135], v[134:135], s[42:43] op_sel:[0,1] op_sel_hi:[1,1]
	v_pk_add_f32 v[136:137], v[136:137], s[42:43] op_sel:[0,1] op_sel_hi:[1,1]
	v_pk_add_f32 v[138:139], v[138:139], s[42:43] op_sel:[0,1] op_sel_hi:[1,1]
	v_rcp_f32_e32 v128, v128
	v_rcp_f32_e32 v129, v129
	v_rcp_f32_e32 v130, v130
	v_rcp_f32_e32 v131, v131
	v_rcp_f32_e32 v176, v132
	v_rcp_f32_e32 v177, v133
	v_rcp_f32_e32 v178, v134
	v_rcp_f32_e32 v179, v135
	v_rcp_f32_e32 v180, v136
	v_rcp_f32_e32 v181, v137
	v_rcp_f32_e32 v182, v138
	v_rcp_f32_e32 v183, v139
	v_min_f32_e32 v132, 0x7149f2ca, v132
	v_min_f32_e32 v133, 0x7149f2ca, v133
	v_min_f32_e32 v134, 0x7149f2ca, v134
	v_min_f32_e32 v135, 0x7149f2ca, v135
	v_min_f32_e32 v136, 0x7149f2ca, v136
	v_min_f32_e32 v137, 0x7149f2ca, v137
	v_min_f32_e32 v138, 0x7149f2ca, v138
	v_min_f32_e32 v139, 0x7149f2ca, v139
	v_pk_mul_f32 v[128:129], v[128:129], v[132:133]
	v_pk_mul_f32 v[130:131], v[130:131], v[134:135]
	v_pk_mul_f32 v[176:177], v[176:177], v[136:137]
	v_pk_mul_f32 v[178:179], v[178:179], v[138:139]
	v_cvt_pk_bf16_f32 v202, v76, v77
	v_cvt_pk_bf16_f32 v203, v78, v79
	v_cvt_pk_bf16_f32 v188, v180, v181
	v_cvt_pk_bf16_f32 v189, v182, v183
	v_cvt_pk_bf16_f32 v184, v128, v129
	v_cvt_pk_bf16_f32 v185, v130, v131
	v_cvt_pk_bf16_f32 v186, v176, v177
	v_cvt_pk_bf16_f32 v187, v178, v179
	global_store_dwordx2 v243, v[184:185], s[98:99] nt
	global_store_dwordx2 v243, v[186:187], s[100:101] nt
	global_store_dwordx2 v243, v[188:189], s[30:31] nt
	s_add_u32 s98, s98, 0x800
	s_addc_u32 s99, s99, 0
	s_add_u32 s100, s100, 0x800
	s_addc_u32 s101, s101, 0
	s_add_u32 s30, s30, 0x800
	s_addc_u32 s31, s31, 0
	v_pk_mul_f32 v[128:129], v[92:93], s[42:43] op_sel_hi:[1,0]
	v_pk_mul_f32 v[130:131], v[94:95], s[42:43] op_sel_hi:[1,0]
	v_pk_mul_f32 v[132:133], v[88:89], s[42:43] op_sel_hi:[1,0]
	v_pk_mul_f32 v[134:135], v[90:91], s[42:43] op_sel_hi:[1,0]
	v_pk_mul_f32 v[136:137], v[64:65], s[42:43] op_sel_hi:[1,0]
	v_pk_mul_f32 v[138:139], v[66:67], s[42:43] op_sel_hi:[1,0]
	v_pk_mul_f32 v[68:69], v[68:69], vcc op_sel_hi:[1,0]
	v_pk_mul_f32 v[70:71], v[70:71], vcc op_sel_hi:[1,0]
	v_exp_f32_e32 v128, v128
	v_exp_f32_e32 v129, v129
	v_exp_f32_e32 v130, v130
	v_exp_f32_e32 v131, v131
	v_exp_f32_e32 v132, v132
	v_exp_f32_e32 v133, v133
	v_exp_f32_e32 v134, v134
	v_exp_f32_e32 v135, v135
	v_exp_f32_e32 v136, v136
	v_exp_f32_e32 v137, v137
	v_exp_f32_e32 v138, v138
	v_exp_f32_e32 v139, v139
	v_pk_add_f32 v[128:129], v[128:129], s[42:43] op_sel:[0,1] op_sel_hi:[1,1]
	v_pk_add_f32 v[130:131], v[130:131], s[42:43] op_sel:[0,1] op_sel_hi:[1,1]
	v_pk_add_f32 v[132:133], v[132:133], s[42:43] op_sel:[0,1] op_sel_hi:[1,1]
	v_pk_add_f32 v[134:135], v[134:135], s[42:43] op_sel:[0,1] op_sel_hi:[1,1]
	v_pk_add_f32 v[136:137], v[136:137], s[42:43] op_sel:[0,1] op_sel_hi:[1,1]
	v_pk_add_f32 v[138:139], v[138:139], s[42:43] op_sel:[0,1] op_sel_hi:[1,1]
	v_rcp_f32_e32 v128, v128
	v_rcp_f32_e32 v129, v129
	v_rcp_f32_e32 v130, v130
	v_rcp_f32_e32 v131, v131
	v_rcp_f32_e32 v176, v132
	v_rcp_f32_e32 v177, v133
	v_rcp_f32_e32 v178, v134
	v_rcp_f32_e32 v179, v135
	v_rcp_f32_e32 v180, v136
	v_rcp_f32_e32 v181, v137
; __device__ __forceinline__ float sigmoidf_(float x) { return __builtin_amdgcn_rcpf(1.0f + __builtin_amdgcn_exp2f(-1.44269504089f * x)); }
; __device__ __forceinline__ u32x2 pk4(f32x4 v) { u32x2 r; r.x = pk_bf16(v[0], v[1]); r.y = pk_bf16(v[2], v[3]); return r; }
; __device__ __forceinline__ int pf(int fq) { return (fq >> 1) | ((fq & 1) << 1); }
;     __device__ __forceinline__ void operator()(const f32x4 (&acc)[2][2][4][2], const Unit& u, int wr, int wc, int fr, int fq) const {
;     ...
;                     for (int m = 0; m < 4; ++m) {
;                         const f32x4 Qv = acc[ai][0][m][0], Ga = acc[ai][0][m][1], Gb = acc[ai][1][m][0], Gx = acc[ai][1][m][1]; f32x4 o1, o2, o3;
; #pragma unroll
;                         for (int j = 0; j < 4; ++j) { const float sa = sigmoidf_(Ga[j]), sb = sigmoidf_(Gb[j]), sx = sigmoidf_(Gx[j]);
;                             o1[j] = sa * __builtin_amdgcn_rcpf(fmaxf(sb, 1e-30f)); o2[j] = sb * __builtin_amdgcn_rcpf(fmaxf(sx, 1e-30f)); o3[j] = sx; }
;                         qv[m] = pk4(Qv * 0.0625f);
;                         const int c = (u.pn & 3) * 64 + wc * 16;
;                         const size_t ns = native_slot(u.pm, (u.pn & 15) >> 2, wr * 4 + ((c >> 5) & 3), ai, m, c >> 7, (c >> 4) & 1, pf(fq) * 16 + fr);
;                         __builtin_nontemporal_store(pk4(o1), (u32x2*)SGA + ns); __builtin_nontemporal_store(pk4(o2), (u32x2*)SGB + ns); __builtin_nontemporal_store(pk4(o3), (u32x2*)SGX + ns);
;                     }
; #pragma unroll
;                     for (int pr = 0; pr < 2; ++pr) store_pair16(Q + (size_t)(rowb + ai * 128 + pr * 32) * 1024 + chw, qv[2 * pr], qv[2 * pr + 1], fq);
	v_rcp_f32_e32 v182, v138
	v_rcp_f32_e32 v183, v139
	v_min_f32_e32 v132, 0x7149f2ca, v132
	v_min_f32_e32 v133, 0x7149f2ca, v133
	v_min_f32_e32 v134, 0x7149f2ca, v134
	v_min_f32_e32 v135, 0x7149f2ca, v135
	v_min_f32_e32 v136, 0x7149f2ca, v136
	v_min_f32_e32 v137, 0x7149f2ca, v137
	v_min_f32_e32 v138, 0x7149f2ca, v138
	v_min_f32_e32 v139, 0x7149f2ca, v139
	v_pk_mul_f32 v[128:129], v[128:129], v[132:133]
	v_pk_mul_f32 v[130:131], v[130:131], v[134:135]
	v_pk_mul_f32 v[176:177], v[176:177], v[136:137]
	v_pk_mul_f32 v[178:179], v[178:179], v[138:139]
	v_cvt_pk_bf16_f32 v204, v68, v69
	v_cvt_pk_bf16_f32 v205, v70, v71
	v_cvt_pk_bf16_f32 v224, v180, v181
	v_cvt_pk_bf16_f32 v225, v182, v183
	v_cvt_pk_bf16_f32 v220, v128, v129
	v_cvt_pk_bf16_f32 v221, v130, v131
	v_cvt_pk_bf16_f32 v222, v176, v177
	v_cvt_pk_bf16_f32 v223, v178, v179
	global_store_dwordx2 v243, v[220:221], s[98:99] nt
	global_store_dwordx2 v243, v[222:223], s[100:101] nt
	global_store_dwordx2 v243, v[224:225], s[30:31] nt
	s_add_u32 s98, s98, 0x800
	s_addc_u32 s99, s99, 0
	s_add_u32 s100, s100, 0x800
	s_addc_u32 s101, s101, 0
	s_add_u32 s30, s30, 0x800
	s_addc_u32 s31, s31, 0
	s_nop 1
	v_permlane32_swap_b32_e32 v198, v200
	v_permlane32_swap_b32_e32 v199, v201
	v_lshl_add_u64 v[248:249], s[46:47], 0, v[246:247]
	global_store_dwordx4 v[248:249], v[198:201], off
	s_nop 1
	v_permlane32_swap_b32_e32 v202, v204
	v_permlane32_swap_b32_e32 v203, v205
	s_mov_b64 s[4:5], 0x10000
	v_lshl_add_u64 v[248:249], v[246:247], 0, s[4:5]
	v_lshl_add_u64 v[248:249], s[46:47], 0, v[248:249]
	global_store_dwordx4 v[248:249], v[202:205], off
	v_pk_mul_f32 v[128:129], v[60:61], s[42:43] op_sel_hi:[1,0]
	v_pk_mul_f32 v[130:131], v[62:63], s[42:43] op_sel_hi:[1,0]
	v_pk_mul_f32 v[132:133], v[56:57], s[42:43] op_sel_hi:[1,0]
	v_pk_mul_f32 v[134:135], v[58:59], s[42:43] op_sel_hi:[1,0]
	v_pk_mul_f32 v[136:137], v[48:49], s[42:43] op_sel_hi:[1,0]
	v_pk_mul_f32 v[138:139], v[50:51], s[42:43] op_sel_hi:[1,0]
	v_pk_mul_f32 v[52:53], v[52:53], vcc op_sel_hi:[1,0]
	v_pk_mul_f32 v[54:55], v[54:55], vcc op_sel_hi:[1,0]
	v_exp_f32_e32 v128, v128
	v_exp_f32_e32 v129, v129
	v_exp_f32_e32 v130, v130
	v_exp_f32_e32 v131, v131
	v_exp_f32_e32 v132, v132
	v_exp_f32_e32 v133, v133
	v_exp_f32_e32 v134, v134
	v_exp_f32_e32 v135, v135
	v_exp_f32_e32 v136, v136
	v_exp_f32_e32 v137, v137
	v_exp_f32_e32 v138, v138
	v_exp_f32_e32 v139, v139
	v_pk_add_f32 v[128:129], v[128:129], s[42:43] op_sel:[0,1] op_sel_hi:[1,1]
	v_pk_add_f32 v[130:131], v[130:131], s[42:43] op_sel:[0,1] op_sel_hi:[1,1]
	v_pk_add_f32 v[132:133], v[132:133], s[42:43] op_sel:[0,1] op_sel_hi:[1,1]
	v_pk_add_f32 v[134:135], v[134:135], s[42:43] op_sel:[0,1] op_sel_hi:[1,1]
	v_pk_add_f32 v[136:137], v[136:137], s[42:43] op_sel:[0,1] op_sel_hi:[1,1]
	v_pk_add_f32 v[138:139], v[138:139], s[42:43] op_sel:[0,1] op_sel_hi:[1,1]
	v_rcp_f32_e32 v128, v128
	v_rcp_f32_e32 v129, v129
	v_rcp_f32_e32 v130, v130
	v_rcp_f32_e32 v131, v131
	v_rcp_f32_e32 v176, v132
	v_rcp_f32_e32 v177, v133
	v_rcp_f32_e32 v178, v134
	v_rcp_f32_e32 v179, v135
	v_rcp_f32_e32 v180, v136
	v_rcp_f32_e32 v181, v137
	v_rcp_f32_e32 v182, v138
	v_rcp_f32_e32 v183, v139
	v_min_f32_e32 v132, 0x7149f2ca, v132
	v_min_f32_e32 v133, 0x7149f2ca, v133
	v_min_f32_e32 v134, 0x7149f2ca, v134
	v_min_f32_e32 v135, 0x7149f2ca, v135
	v_min_f32_e32 v136, 0x7149f2ca, v136
	v_min_f32_e32 v137, 0x7149f2ca, v137
	v_min_f32_e32 v138, 0x7149f2ca, v138
	v_min_f32_e32 v139, 0x7149f2ca, v139
	v_pk_mul_f32 v[128:129], v[128:129], v[132:133]
	v_pk_mul_f32 v[130:131], v[130:131], v[134:135]
	v_pk_mul_f32 v[176:177], v[176:177], v[136:137]
	v_pk_mul_f32 v[178:179], v[178:179], v[138:139]
	v_cvt_pk_bf16_f32 v198, v52, v53
	v_cvt_pk_bf16_f32 v199, v54, v55
	v_cvt_pk_bf16_f32 v188, v180, v181
	v_cvt_pk_bf16_f32 v189, v182, v183
	v_cvt_pk_bf16_f32 v184, v128, v129
	v_cvt_pk_bf16_f32 v185, v130, v131
	v_cvt_pk_bf16_f32 v186, v176, v177
	v_cvt_pk_bf16_f32 v187, v178, v179
	global_store_dwordx2 v243, v[184:185], s[98:99] nt
	global_store_dwordx2 v243, v[186:187], s[100:101] nt
	global_store_dwordx2 v243, v[188:189], s[30:31] nt
	s_add_u32 s98, s98, 0x800
	s_addc_u32 s99, s99, 0
	s_add_u32 s100, s100, 0x800
	s_addc_u32 s101, s101, 0
	s_add_u32 s30, s30, 0x800
	s_addc_u32 s31, s31, 0
	v_pk_mul_f32 v[128:129], v[44:45], s[42:43] op_sel_hi:[1,0]
	v_pk_mul_f32 v[130:131], v[46:47], s[42:43] op_sel_hi:[1,0]
	v_pk_mul_f32 v[132:133], v[40:41], s[42:43] op_sel_hi:[1,0]
	v_pk_mul_f32 v[134:135], v[42:43], s[42:43] op_sel_hi:[1,0]
	v_pk_mul_f32 v[136:137], v[16:17], s[42:43] op_sel_hi:[1,0]
	v_pk_mul_f32 v[138:139], v[18:19], s[42:43] op_sel_hi:[1,0]
	v_pk_mul_f32 v[20:21], v[20:21], vcc op_sel_hi:[1,0]
	v_pk_mul_f32 v[22:23], v[22:23], vcc op_sel_hi:[1,0]
	v_exp_f32_e32 v128, v128
	v_exp_f32_e32 v129, v129
	v_exp_f32_e32 v130, v130
	v_exp_f32_e32 v131, v131
	v_exp_f32_e32 v132, v132
	v_exp_f32_e32 v133, v133
	v_exp_f32_e32 v134, v134
	v_exp_f32_e32 v135, v135
	v_exp_f32_e32 v136, v136
	v_exp_f32_e32 v137, v137
	v_exp_f32_e32 v138, v138
	v_exp_f32_e32 v139, v139
	v_pk_add_f32 v[128:129], v[128:129], s[42:43] op_sel:[0,1] op_sel_hi:[1,1]
	v_pk_add_f32 v[130:131], v[130:131], s[42:43] op_sel:[0,1] op_sel_hi:[1,1]
	v_pk_add_f32 v[132:133], v[132:133], s[42:43] op_sel:[0,1] op_sel_hi:[1,1]
	v_pk_add_f32 v[134:135], v[134:135], s[42:43] op_sel:[0,1] op_sel_hi:[1,1]
	v_pk_add_f32 v[136:137], v[136:137], s[42:43] op_sel:[0,1] op_sel_hi:[1,1]
	v_pk_add_f32 v[138:139], v[138:139], s[42:43] op_sel:[0,1] op_sel_hi:[1,1]
	v_rcp_f32_e32 v128, v128
	v_rcp_f32_e32 v129, v129
	v_rcp_f32_e32 v130, v130
	v_rcp_f32_e32 v131, v131
	v_rcp_f32_e32 v176, v132
; __device__ __forceinline__ float sigmoidf_(float x) { return __builtin_amdgcn_rcpf(1.0f + __builtin_amdgcn_exp2f(-1.44269504089f * x)); }
; __device__ __forceinline__ u32x2 pk4(f32x4 v) { u32x2 r; r.x = pk_bf16(v[0], v[1]); r.y = pk_bf16(v[2], v[3]); return r; }
; __device__ __forceinline__ int pf(int fq) { return (fq >> 1) | ((fq & 1) << 1); }
;     __device__ __forceinline__ void operator()(const f32x4 (&acc)[2][2][4][2], const Unit& u, int wr, int wc, int fr, int fq) const {
;     ...
;                     for (int m = 0; m < 4; ++m) {
;                         const f32x4 Qv = acc[ai][0][m][0], Ga = acc[ai][0][m][1], Gb = acc[ai][1][m][0], Gx = acc[ai][1][m][1]; f32x4 o1, o2, o3;
; #pragma unroll
;                         for (int j = 0; j < 4; ++j) { const float sa = sigmoidf_(Ga[j]), sb = sigmoidf_(Gb[j]), sx = sigmoidf_(Gx[j]);
;                             o1[j] = sa * __builtin_amdgcn_rcpf(fmaxf(sb, 1e-30f)); o2[j] = sb * __builtin_amdgcn_rcpf(fmaxf(sx, 1e-30f)); o3[j] = sx; }
;                         qv[m] = pk4(Qv * 0.0625f);
;                         const int c = (u.pn & 3) * 64 + wc * 16;
;                         const size_t ns = native_slot(u.pm, (u.pn & 15) >> 2, wr * 4 + ((c >> 5) & 3), ai, m, c >> 7, (c >> 4) & 1, pf(fq) * 16 + fr);
;                         __builtin_nontemporal_store(pk4(o1), (u32x2*)SGA + ns); __builtin_nontemporal_store(pk4(o2), (u32x2*)SGB + ns); __builtin_nontemporal_store(pk4(o3), (u32x2*)SGX + ns);
;                     }
	v_rcp_f32_e32 v177, v133
	v_rcp_f32_e32 v178, v134
	v_rcp_f32_e32 v179, v135
	v_rcp_f32_e32 v180, v136
	v_rcp_f32_e32 v181, v137
	v_rcp_f32_e32 v182, v138
	v_rcp_f32_e32 v183, v139
	v_min_f32_e32 v132, 0x7149f2ca, v132
	v_min_f32_e32 v133, 0x7149f2ca, v133
	v_min_f32_e32 v134, 0x7149f2ca, v134
	v_min_f32_e32 v135, 0x7149f2ca, v135
	v_min_f32_e32 v136, 0x7149f2ca, v136
	v_min_f32_e32 v137, 0x7149f2ca, v137
	v_min_f32_e32 v138, 0x7149f2ca, v138
	v_min_f32_e32 v139, 0x7149f2ca, v139
	v_pk_mul_f32 v[128:129], v[128:129], v[132:133]
	v_pk_mul_f32 v[130:131], v[130:131], v[134:135]
	v_pk_mul_f32 v[176:177], v[176:177], v[136:137]
	v_pk_mul_f32 v[178:179], v[178:179], v[138:139]
	v_cvt_pk_bf16_f32 v200, v20, v21
	v_cvt_pk_bf16_f32 v201, v22, v23
	v_cvt_pk_bf16_f32 v224, v180, v181
	v_cvt_pk_bf16_f32 v225, v182, v183
	v_cvt_pk_bf16_f32 v220, v128, v129
	v_cvt_pk_bf16_f32 v221, v130, v131
	v_cvt_pk_bf16_f32 v222, v176, v177
	v_cvt_pk_bf16_f32 v223, v178, v179
	global_store_dwordx2 v243, v[220:221], s[98:99] nt
	global_store_dwordx2 v243, v[222:223], s[100:101] nt
	global_store_dwordx2 v243, v[224:225], s[30:31] nt
	s_add_u32 s98, s98, 0x800
	s_addc_u32 s99, s99, 0
	s_add_u32 s100, s100, 0x800
	s_addc_u32 s101, s101, 0
	s_add_u32 s30, s30, 0x800
	s_addc_u32 s31, s31, 0
	v_pk_mul_f32 v[128:129], v[36:37], s[42:43] op_sel_hi:[1,0]
	v_pk_mul_f32 v[130:131], v[38:39], s[42:43] op_sel_hi:[1,0]
	v_pk_mul_f32 v[132:133], v[32:33], s[42:43] op_sel_hi:[1,0]
	v_pk_mul_f32 v[134:135], v[34:35], s[42:43] op_sel_hi:[1,0]
	v_pk_mul_f32 v[136:137], v[8:9], s[42:43] op_sel_hi:[1,0]
	v_pk_mul_f32 v[138:139], v[10:11], s[42:43] op_sel_hi:[1,0]
	v_pk_mul_f32 v[12:13], v[12:13], vcc op_sel_hi:[1,0]
	v_pk_mul_f32 v[14:15], v[14:15], vcc op_sel_hi:[1,0]
	v_exp_f32_e32 v128, v128
	v_exp_f32_e32 v129, v129
	v_exp_f32_e32 v130, v130
	v_exp_f32_e32 v131, v131
	v_exp_f32_e32 v132, v132
	v_exp_f32_e32 v133, v133
	v_exp_f32_e32 v134, v134
	v_exp_f32_e32 v135, v135
	v_exp_f32_e32 v136, v136
	v_exp_f32_e32 v137, v137
	v_exp_f32_e32 v138, v138
	v_exp_f32_e32 v139, v139
	v_pk_add_f32 v[128:129], v[128:129], s[42:43] op_sel:[0,1] op_sel_hi:[1,1]
	v_pk_add_f32 v[130:131], v[130:131], s[42:43] op_sel:[0,1] op_sel_hi:[1,1]
	v_pk_add_f32 v[132:133], v[132:133], s[42:43] op_sel:[0,1] op_sel_hi:[1,1]
	v_pk_add_f32 v[134:135], v[134:135], s[42:43] op_sel:[0,1] op_sel_hi:[1,1]
	v_pk_add_f32 v[136:137], v[136:137], s[42:43] op_sel:[0,1] op_sel_hi:[1,1]
	v_pk_add_f32 v[138:139], v[138:139], s[42:43] op_sel:[0,1] op_sel_hi:[1,1]
	v_rcp_f32_e32 v128, v128
	v_rcp_f32_e32 v129, v129
	v_rcp_f32_e32 v130, v130
	v_rcp_f32_e32 v131, v131
	v_rcp_f32_e32 v176, v132
	v_rcp_f32_e32 v177, v133
	v_rcp_f32_e32 v178, v134
	v_rcp_f32_e32 v179, v135
	v_rcp_f32_e32 v180, v136
	v_rcp_f32_e32 v181, v137
	v_rcp_f32_e32 v182, v138
	v_rcp_f32_e32 v183, v139
	v_min_f32_e32 v132, 0x7149f2ca, v132
	v_min_f32_e32 v133, 0x7149f2ca, v133
	v_min_f32_e32 v134, 0x7149f2ca, v134
	v_min_f32_e32 v135, 0x7149f2ca, v135
	v_min_f32_e32 v136, 0x7149f2ca, v136
	v_min_f32_e32 v137, 0x7149f2ca, v137
	v_min_f32_e32 v138, 0x7149f2ca, v138
	v_min_f32_e32 v139, 0x7149f2ca, v139
	v_pk_mul_f32 v[128:129], v[128:129], v[132:133]
	v_pk_mul_f32 v[130:131], v[130:131], v[134:135]
	v_pk_mul_f32 v[176:177], v[176:177], v[136:137]
	v_pk_mul_f32 v[178:179], v[178:179], v[138:139]
	v_cvt_pk_bf16_f32 v202, v12, v13
	v_cvt_pk_bf16_f32 v203, v14, v15
	v_cvt_pk_bf16_f32 v188, v180, v181
	v_cvt_pk_bf16_f32 v189, v182, v183
	v_cvt_pk_bf16_f32 v184, v128, v129
	v_cvt_pk_bf16_f32 v185, v130, v131
; __device__ __forceinline__ float sigmoidf_(float x) { return __builtin_amdgcn_rcpf(1.0f + __builtin_amdgcn_exp2f(-1.44269504089f * x)); }
; __device__ __forceinline__ u32x2 pk4(f32x4 v) { u32x2 r; r.x = pk_bf16(v[0], v[1]); r.y = pk_bf16(v[2], v[3]); return r; }
; __device__ __forceinline__ int pf(int fq) { return (fq >> 1) | ((fq & 1) << 1); }
;     __device__ __forceinline__ void operator()(const f32x4 (&acc)[2][2][4][2], const Unit& u, int wr, int wc, int fr, int fq) const {
;     ...
;                     for (int m = 0; m < 4; ++m) {
;                         const f32x4 Qv = acc[ai][0][m][0], Ga = acc[ai][0][m][1], Gb = acc[ai][1][m][0], Gx = acc[ai][1][m][1]; f32x4 o1, o2, o3;
; #pragma unroll
;                         for (int j = 0; j < 4; ++j) { const float sa = sigmoidf_(Ga[j]), sb = sigmoidf_(Gb[j]), sx = sigmoidf_(Gx[j]);
;                             o1[j] = sa * __builtin_amdgcn_rcpf(fmaxf(sb, 1e-30f)); o2[j] = sb * __builtin_amdgcn_rcpf(fmaxf(sx, 1e-30f)); o3[j] = sx; }
;                         qv[m] = pk4(Qv * 0.0625f);
;                         const int c = (u.pn & 3) * 64 + wc * 16;
;                         const size_t ns = native_slot(u.pm, (u.pn & 15) >> 2, wr * 4 + ((c >> 5) & 3), ai, m, c >> 7, (c >> 4) & 1, pf(fq) * 16 + fr);
;                         __builtin_nontemporal_store(pk4(o1), (u32x2*)SGA + ns); __builtin_nontemporal_store(pk4(o2), (u32x2*)SGB + ns); __builtin_nontemporal_store(pk4(o3), (u32x2*)SGX + ns);
;                     }
; #pragma unroll
;                     for (int pr = 0; pr < 2; ++pr) store_pair16(Q + (size_t)(rowb + ai * 128 + pr * 32) * 1024 + chw, qv[2 * pr], qv[2 * pr + 1], fq);
	v_cvt_pk_bf16_f32 v186, v176, v177
	v_cvt_pk_bf16_f32 v187, v178, v179
	global_store_dwordx2 v243, v[184:185], s[98:99] nt
	global_store_dwordx2 v243, v[186:187], s[100:101] nt
	global_store_dwordx2 v243, v[188:189], s[30:31] nt
	s_add_u32 s98, s98, 0x800
	s_addc_u32 s99, s99, 0
	s_add_u32 s100, s100, 0x800
	s_addc_u32 s101, s101, 0
	s_add_u32 s30, s30, 0x800
	s_addc_u32 s31, s31, 0
	v_pk_mul_f32 v[128:129], v[28:29], s[42:43] op_sel_hi:[1,0]
	v_pk_mul_f32 v[130:131], v[30:31], s[42:43] op_sel_hi:[1,0]
	v_pk_mul_f32 v[132:133], v[24:25], s[42:43] op_sel_hi:[1,0]
	v_pk_mul_f32 v[134:135], v[26:27], s[42:43] op_sel_hi:[1,0]
	v_pk_mul_f32 v[136:137], v[0:1], s[42:43] op_sel_hi:[1,0]
	v_pk_mul_f32 v[138:139], v[2:3], s[42:43] op_sel_hi:[1,0]
	v_pk_mul_f32 v[4:5], v[4:5], vcc op_sel_hi:[1,0]
	v_pk_mul_f32 v[6:7], v[6:7], vcc op_sel_hi:[1,0]
	v_exp_f32_e32 v128, v128
	v_exp_f32_e32 v129, v129
	v_exp_f32_e32 v130, v130
	v_exp_f32_e32 v131, v131
	v_exp_f32_e32 v132, v132
	v_exp_f32_e32 v133, v133
	v_exp_f32_e32 v134, v134
	v_exp_f32_e32 v135, v135
	v_exp_f32_e32 v136, v136
	v_exp_f32_e32 v137, v137
	v_exp_f32_e32 v138, v138
	v_exp_f32_e32 v139, v139
	v_pk_add_f32 v[128:129], v[128:129], s[42:43] op_sel:[0,1] op_sel_hi:[1,1]
	v_pk_add_f32 v[130:131], v[130:131], s[42:43] op_sel:[0,1] op_sel_hi:[1,1]
	v_pk_add_f32 v[132:133], v[132:133], s[42:43] op_sel:[0,1] op_sel_hi:[1,1]
	v_pk_add_f32 v[134:135], v[134:135], s[42:43] op_sel:[0,1] op_sel_hi:[1,1]
	v_pk_add_f32 v[136:137], v[136:137], s[42:43] op_sel:[0,1] op_sel_hi:[1,1]
	v_pk_add_f32 v[138:139], v[138:139], s[42:43] op_sel:[0,1] op_sel_hi:[1,1]
	v_rcp_f32_e32 v128, v128
	v_rcp_f32_e32 v129, v129
	v_rcp_f32_e32 v130, v130
	v_rcp_f32_e32 v131, v131
	v_rcp_f32_e32 v176, v132
	v_rcp_f32_e32 v177, v133
	v_rcp_f32_e32 v178, v134
	v_rcp_f32_e32 v179, v135
	v_rcp_f32_e32 v180, v136
	v_rcp_f32_e32 v181, v137
	v_rcp_f32_e32 v182, v138
	v_rcp_f32_e32 v183, v139
	v_min_f32_e32 v132, 0x7149f2ca, v132
	v_min_f32_e32 v133, 0x7149f2ca, v133
	v_min_f32_e32 v134, 0x7149f2ca, v134
	v_min_f32_e32 v135, 0x7149f2ca, v135
	v_min_f32_e32 v136, 0x7149f2ca, v136
	v_min_f32_e32 v137, 0x7149f2ca, v137
	v_min_f32_e32 v138, 0x7149f2ca, v138
	v_min_f32_e32 v139, 0x7149f2ca, v139
	v_pk_mul_f32 v[128:129], v[128:129], v[132:133]
	v_pk_mul_f32 v[130:131], v[130:131], v[134:135]
	v_pk_mul_f32 v[176:177], v[176:177], v[136:137]
	v_pk_mul_f32 v[178:179], v[178:179], v[138:139]
	v_cvt_pk_bf16_f32 v204, v4, v5
	v_cvt_pk_bf16_f32 v205, v6, v7
	v_cvt_pk_bf16_f32 v224, v180, v181
	v_cvt_pk_bf16_f32 v225, v182, v183
	v_cvt_pk_bf16_f32 v220, v128, v129
	v_cvt_pk_bf16_f32 v221, v130, v131
	v_cvt_pk_bf16_f32 v222, v176, v177
	v_cvt_pk_bf16_f32 v223, v178, v179
	global_store_dwordx2 v243, v[220:221], s[98:99] nt
	global_store_dwordx2 v243, v[222:223], s[100:101] nt
	global_store_dwordx2 v243, v[224:225], s[30:31] nt
	s_add_u32 s98, s98, 0x800
	s_addc_u32 s99, s99, 0
	s_add_u32 s100, s100, 0x800
	s_addc_u32 s101, s101, 0
	s_add_u32 s30, s30, 0x800
	s_addc_u32 s31, s31, 0
	s_nop 1
	v_permlane32_swap_b32_e32 v198, v200
	v_permlane32_swap_b32_e32 v199, v201
	s_mov_b64 s[4:5], 0x40000
	v_lshl_add_u64 v[248:249], v[246:247], 0, s[4:5]
	v_lshl_add_u64 v[248:249], s[46:47], 0, v[248:249]
	global_store_dwordx4 v[248:249], v[198:201], off
	s_nop 1
	v_permlane32_swap_b32_e32 v202, v204
	v_permlane32_swap_b32_e32 v203, v205
	s_mov_b64 s[4:5], 0x50000
	v_lshl_add_u64 v[248:249], v[246:247], 0, s[4:5]
	v_lshl_add_u64 v[248:249], s[46:47], 0, v[248:249]
	global_store_dwordx4 v[248:249], v[202:205], off
	s_branch .LBB0_287

; __device__ __forceinline__ u32x2 pk4(f32x4 v) { u32x2 r; r.x = pk_bf16(v[0], v[1]); r.y = pk_bf16(v[2], v[3]); return r; }
; __device__ __forceinline__ f32x4 unpk4(u32x2 v) { return (f32x4){bf_lo(v.x), bf_hi(v.x), bf_lo(v.y), bf_hi(v.y)}; }
;     __device__ __forceinline__ void operator()(const f32x4 (&acc)[2][2][4][2], const Unit& u, int wr, int wc, int fr, int fq) const {
; #pragma unroll
;         for (int ai = 0; ai < 2; ++ai)
; #pragma unroll
;             for (int m = 0; m < 4; ++m) {
;                 const int row = u.pm * 256 + ai * 128 + wr * 64 + m * 16 + fr; float rs = 0.f;
; #pragma unroll
;                 for (int bj = 0; bj < 2; ++bj)
; #pragma unroll
;                     for (int n = 0; n < 2; ++n) {
;                         const f32x4 s = acc[ai][bj][m][n]; f32x4 e;
; #pragma unroll
;                         for (int j = 0; j < 4; ++j) e[j] = __builtin_amdgcn_exp2f(1.44269504089f * s[j]);
;                         const u32x2 w = pk4(e); const f32x4 er = unpk4(w); rs += (er[0] + er[1]) + (er[2] + er[3]);
;                         *(u32x2*)(Q + (size_t)row * 1024 + u.pn * 256 + bj * 128 + wc * 32 + n * 16 + fq * 4) = w;
;                     }
;                 rs += __shfl_xor(rs, 16); rs += __shfl_xor(rs, 32);
;                 if (fq == 0) unsafeAtomicAdd(RSUM + row * 4 + u.pn, rs);
;             }
.LBB0_365:
	v_lshrrev_b32_e32 v250, 1, v147
	v_and_b32_e32 v250, 24, v250
	v_mov_b32_e32 v251, 0
	v_and_b32_e32 v135, 64, v147
	v_xor_b32_e32 v134, 16, v147
	v_add_u32_e32 v135, 64, v135
	v_exp_f32_e32 v138, v124
	v_cmp_lt_i32_e32 vcc, v134, v135
	v_exp_f32_e32 v139, v125
	v_cndmask_b32_e32 v134, v147, v134, vcc
	v_exp_f32_e32 v152, v126
	v_lshlrev_b32_e32 v151, 2, v134
	v_xor_b32_e32 v134, 32, v147
	v_exp_f32_e32 v127, v127
	v_cmp_lt_i32_e32 vcc, v134, v135
	s_lshl_b32 s67, s28, 8
	v_cvt_pk_bf16_f32 v126, v138, v139
	v_cndmask_b32_e32 v134, v147, v134, vcc
	v_lshlrev_b32_e32 v150, 2, v134
	v_add_u32_e32 v134, s67, v136
	v_ashrrev_i32_e32 v135, 31, v134
	v_cvt_pk_bf16_f32 v127, v152, v127
	v_lshlrev_b64 v[124:125], 11, v[134:135]
	v_lshlrev_b32_e32 v135, 16, v126
	v_and_b32_e32 v138, 0xffff0000, v126
	v_lshlrev_b32_e32 v139, 16, v127
	v_and_b32_e32 v152, 0xffff0000, v127
	v_add_f32_e32 v135, v135, v138
	v_add_f32_e32 v138, v139, v152
	v_add_f32_e32 v135, v135, v138
	v_exp_f32_e32 v138, v120
	v_exp_f32_e32 v139, v121
	v_exp_f32_e32 v152, v122
	v_exp_f32_e32 v123, v123
	v_exp_f32_e32 v116, v116
	v_exp_f32_e32 v117, v117
	v_exp_f32_e32 v118, v118
	v_exp_f32_e32 v119, v119
	v_cvt_pk_bf16_f32 v122, v138, v139
	v_cvt_pk_bf16_f32 v123, v152, v123
	v_lshl_add_u64 v[120:121], s[46:47], 0, v[124:125]
	v_lshlrev_b32_e32 v124, 16, v122
	v_and_b32_e32 v125, 0xffff0000, v122
	v_lshlrev_b32_e32 v138, 16, v123
	v_and_b32_e32 v139, 0xffff0000, v123
	v_add_f32_e32 v124, v124, v125
	v_add_f32_e32 v125, v138, v139
	v_add_f32_e32 v135, 0, v135
	v_add_f32_e32 v124, v124, v125
	v_cvt_pk_bf16_f32 v116, v116, v117
	v_cvt_pk_bf16_f32 v117, v118, v119
	v_add_f32_e32 v124, v135, v124
	v_lshlrev_b32_e32 v118, 16, v116
	v_and_b32_e32 v119, 0xffff0000, v116
	v_lshlrev_b32_e32 v125, 16, v117
	v_and_b32_e32 v135, 0xffff0000, v117
	v_add_f32_e32 v118, v118, v119
	v_add_f32_e32 v119, v125, v135
	v_exp_f32_e32 v125, v114
	v_exp_f32_e32 v112, v112
	v_exp_f32_e32 v113, v113
	v_exp_f32_e32 v115, v115
	v_add_f32_e32 v114, v118, v119
	v_add_f32_e32 v118, v124, v114
	v_cvt_pk_bf16_f32 v114, v112, v113
	v_cvt_pk_bf16_f32 v115, v125, v115
	v_lshlrev_b32_e32 v112, 16, v114
	v_and_b32_e32 v113, 0xffff0000, v114
	v_lshlrev_b32_e32 v119, 16, v115
	v_and_b32_e32 v124, 0xffff0000, v115
	v_add_f32_e32 v112, v112, v113
	v_add_f32_e32 v113, v119, v124
	v_add_f32_e32 v112, v112, v113
	v_add_f32_e32 v124, v118, v112
	ds_bpermute_b32 v125, v151, v124
	s_lshl_b32 s74, s30, 8
	s_ashr_i32 s75, s74, 31
	v_lshl_add_u64 v[112:113], s[74:75], 1, v[120:121]
	v_lshl_add_u64 v[112:113], v[112:113], 0, s[54:55]
	v_lshl_add_u64 v[118:119], v[112:113], 0, v[132:133]
	s_waitcnt lgkmcnt(0)
	v_add_f32_e32 v112, v124, v125
	ds_bpermute_b32 v113, v150, v112
	v_mov_b32_e32 v200, v126
	v_mov_b32_e32 v201, v127
	v_mov_b32_e32 v202, v122
	v_mov_b32_e32 v203, v123
	v_mov_b32_e32 v204, v116
	v_mov_b32_e32 v205, v117
	v_mov_b32_e32 v206, v114
	v_mov_b32_e32 v207, v115
	v_permlane32_swap_b32_e32 v200, v202
	v_permlane32_swap_b32_e32 v201, v203
	v_permlane32_swap_b32_e32 v204, v206
	v_permlane32_swap_b32_e32 v205, v207
	v_permlane16_swap_b32_e32 v200, v202
	v_permlane16_swap_b32_e32 v201, v203
	v_permlane16_swap_b32_e32 v204, v206
	v_permlane16_swap_b32_e32 v205, v207
	v_lshl_add_u64 v[208:209], v[118:119], 0, v[250:251]
	global_store_dwordx4 v[208:209], v[200:203], off
	global_store_dwordx4 v[208:209], v[204:207], off offset:256
	s_and_saveexec_b64 s[28:29], s[6:7]
	s_cbranch_execz .LBB0_367
	s_waitcnt lgkmcnt(0)
	v_add_f32_e32 v114, v112, v113
	v_lshlrev_b32_e32 v112, 2, v134
	v_ashrrev_i32_e32 v113, 31, v112
	v_lshl_add_u64 v[112:113], v[112:113], 2, s[44:45]
	s_ashr_i32 s31, s30, 31
	v_lshl_add_u64 v[112:113], s[30:31], 2, v[112:113]
	global_atomic_add_f32 v[112:113], v114, off
.LBB0_367:
	s_or_b64 exec, exec, s[28:29]
	v_exp_f32_e32 v114, v108
	v_exp_f32_e32 v115, v109
	v_exp_f32_e32 v116, v110
	v_exp_f32_e32 v111, v111
	v_or_b32_e32 v112, 16, v136
	v_exp_f32_e32 v104, v104
	v_exp_f32_e32 v105, v105
	v_exp_f32_e32 v106, v106
	v_exp_f32_e32 v107, v107
	v_add_u32_e32 v112, s67, v112
	s_waitcnt lgkmcnt(0)
	v_ashrrev_i32_e32 v113, 31, v112
	v_cvt_pk_bf16_f32 v110, v114, v115
	v_cvt_pk_bf16_f32 v111, v116, v111
	v_lshlrev_b64 v[108:109], 11, v[112:113]
	v_lshlrev_b32_e32 v113, 16, v110
	v_and_b32_e32 v114, 0xffff0000, v110
	v_lshlrev_b32_e32 v115, 16, v111
	v_and_b32_e32 v116, 0xffff0000, v111
	v_exp_f32_e32 v100, v100
	v_exp_f32_e32 v101, v101
	v_exp_f32_e32 v102, v102
	v_exp_f32_e32 v103, v103
	v_add_f32_e32 v113, v113, v114
	v_add_f32_e32 v114, v115, v116
	v_cvt_pk_bf16_f32 v104, v104, v105
	v_cvt_pk_bf16_f32 v105, v106, v107
	v_add_f32_e32 v113, v113, v114
	v_lshlrev_b32_e32 v106, 16, v104
	v_and_b32_e32 v107, 0xffff0000, v104
	v_lshlrev_b32_e32 v114, 16, v105
	v_and_b32_e32 v115, 0xffff0000, v105
	v_add_f32_e32 v106, v106, v107
	v_add_f32_e32 v107, v114, v115
	v_add_f32_e32 v113, 0, v113
	v_add_f32_e32 v106, v106, v107
	v_cvt_pk_bf16_f32 v100, v100, v101
	v_cvt_pk_bf16_f32 v101, v102, v103
	v_add_f32_e32 v106, v113, v106
	v_lshlrev_b32_e32 v102, 16, v100
	v_and_b32_e32 v103, 0xffff0000, v100
	v_lshlrev_b32_e32 v107, 16, v101
	v_and_b32_e32 v113, 0xffff0000, v101
	v_add_f32_e32 v102, v102, v103
	v_add_f32_e32 v103, v107, v113
	v_exp_f32_e32 v107, v98
	v_exp_f32_e32 v96, v96
	v_exp_f32_e32 v97, v97
	v_exp_f32_e32 v99, v99
	v_add_f32_e32 v98, v102, v103
	v_add_f32_e32 v102, v106, v98
	v_cvt_pk_bf16_f32 v98, v96, v97
	v_cvt_pk_bf16_f32 v99, v107, v99
	v_lshlrev_b32_e32 v96, 16, v98
	v_and_b32_e32 v97, 0xffff0000, v98
	v_lshlrev_b32_e32 v103, 16, v99
	v_and_b32_e32 v106, 0xffff0000, v99
	v_add_f32_e32 v96, v96, v97
	v_add_f32_e32 v97, v103, v106
	v_add_f32_e32 v96, v96, v97
	v_add_f32_e32 v106, v102, v96
	ds_bpermute_b32 v107, v151, v106
	v_lshl_add_u64 v[96:97], s[46:47], 0, v[108:109]
	v_lshl_add_u64 v[96:97], s[74:75], 1, v[96:97]
	v_lshl_add_u64 v[96:97], v[96:97], 0, s[54:55]
	v_lshl_add_u64 v[102:103], v[96:97], 0, v[132:133]
	s_waitcnt lgkmcnt(0)
	v_add_f32_e32 v96, v106, v107
	ds_bpermute_b32 v97, v150, v96
	v_mov_b32_e32 v212, v110
	v_mov_b32_e32 v213, v111
	v_mov_b32_e32 v214, v104
	v_mov_b32_e32 v215, v105
	v_mov_b32_e32 v216, v100
	v_mov_b32_e32 v217, v101
	v_mov_b32_e32 v218, v98
	v_mov_b32_e32 v219, v99
	v_permlane32_swap_b32_e32 v212, v214
	v_permlane32_swap_b32_e32 v213, v215
	v_permlane32_swap_b32_e32 v216, v218
	v_permlane32_swap_b32_e32 v217, v219
	v_permlane16_swap_b32_e32 v212, v214
	v_permlane16_swap_b32_e32 v213, v215
	v_permlane16_swap_b32_e32 v216, v218
	v_permlane16_swap_b32_e32 v217, v219
	v_lshl_add_u64 v[208:209], v[102:103], 0, v[250:251]
	global_store_dwordx4 v[208:209], v[212:215], off
	global_store_dwordx4 v[208:209], v[216:219], off offset:256
	s_and_saveexec_b64 s[28:29], s[6:7]
	s_cbranch_execz .LBB0_369
; __device__ __forceinline__ u32x2 pk4(f32x4 v) { u32x2 r; r.x = pk_bf16(v[0], v[1]); r.y = pk_bf16(v[2], v[3]); return r; }
; __device__ __forceinline__ f32x4 unpk4(u32x2 v) { return (f32x4){bf_lo(v.x), bf_hi(v.x), bf_lo(v.y), bf_hi(v.y)}; }
;     __device__ __forceinline__ void operator()(const f32x4 (&acc)[2][2][4][2], const Unit& u, int wr, int wc, int fr, int fq) const {
; #pragma unroll
;         for (int ai = 0; ai < 2; ++ai)
; #pragma unroll
;             for (int m = 0; m < 4; ++m) {
;                 const int row = u.pm * 256 + ai * 128 + wr * 64 + m * 16 + fr; float rs = 0.f;
; #pragma unroll
;                 for (int bj = 0; bj < 2; ++bj)
; #pragma unroll
;                     for (int n = 0; n < 2; ++n) {
;                         const f32x4 s = acc[ai][bj][m][n]; f32x4 e;
; #pragma unroll
;                         for (int j = 0; j < 4; ++j) e[j] = __builtin_amdgcn_exp2f(1.44269504089f * s[j]);
;                         const u32x2 w = pk4(e); const f32x4 er = unpk4(w); rs += (er[0] + er[1]) + (er[2] + er[3]);
;                         *(u32x2*)(Q + (size_t)row * 1024 + u.pn * 256 + bj * 128 + wc * 32 + n * 16 + fq * 4) = w;
;                     }
;                 rs += __shfl_xor(rs, 16); rs += __shfl_xor(rs, 32);
;                 if (fq == 0) unsafeAtomicAdd(RSUM + row * 4 + u.pn, rs);
;             }
	s_waitcnt lgkmcnt(0)
	v_add_f32_e32 v98, v96, v97
	v_lshlrev_b32_e32 v96, 2, v112
	v_ashrrev_i32_e32 v97, 31, v96
	v_lshl_add_u64 v[96:97], v[96:97], 2, s[44:45]
	s_ashr_i32 s31, s30, 31
	v_lshl_add_u64 v[96:97], s[30:31], 2, v[96:97]
	global_atomic_add_f32 v[96:97], v98, off
.LBB0_369:
	s_or_b64 exec, exec, s[28:29]
	v_exp_f32_e32 v98, v92
	v_exp_f32_e32 v99, v93
	v_exp_f32_e32 v100, v94
	v_exp_f32_e32 v95, v95
	v_exp_f32_e32 v88, v88
	v_exp_f32_e32 v89, v89
	v_exp_f32_e32 v90, v90
	v_exp_f32_e32 v91, v91
	v_add_u32_e32 v96, s67, v254
	s_waitcnt lgkmcnt(0)
	v_ashrrev_i32_e32 v97, 31, v96
	v_cvt_pk_bf16_f32 v94, v98, v99
	v_cvt_pk_bf16_f32 v95, v100, v95
	v_lshlrev_b64 v[92:93], 11, v[96:97]
	v_lshlrev_b32_e32 v97, 16, v94
	v_and_b32_e32 v98, 0xffff0000, v94
	v_lshlrev_b32_e32 v99, 16, v95
	v_and_b32_e32 v100, 0xffff0000, v95
	v_exp_f32_e32 v84, v84
	v_exp_f32_e32 v85, v85
	v_exp_f32_e32 v86, v86
	v_exp_f32_e32 v87, v87
	v_add_f32_e32 v97, v97, v98
	v_add_f32_e32 v98, v99, v100
	v_cvt_pk_bf16_f32 v88, v88, v89
	v_cvt_pk_bf16_f32 v89, v90, v91
	v_add_f32_e32 v97, v97, v98
	v_lshlrev_b32_e32 v90, 16, v88
	v_and_b32_e32 v91, 0xffff0000, v88
	v_lshlrev_b32_e32 v98, 16, v89
	v_and_b32_e32 v99, 0xffff0000, v89
	v_add_f32_e32 v90, v90, v91
	v_add_f32_e32 v91, v98, v99
	v_add_f32_e32 v97, 0, v97
	v_add_f32_e32 v90, v90, v91
	v_cvt_pk_bf16_f32 v84, v84, v85
	v_cvt_pk_bf16_f32 v85, v86, v87
	v_add_f32_e32 v90, v97, v90
	v_lshlrev_b32_e32 v86, 16, v84
	v_and_b32_e32 v87, 0xffff0000, v84
	v_lshlrev_b32_e32 v91, 16, v85
	v_and_b32_e32 v97, 0xffff0000, v85
	v_add_f32_e32 v86, v86, v87
	v_add_f32_e32 v87, v91, v97
	v_exp_f32_e32 v91, v82
	v_exp_f32_e32 v80, v80
	v_exp_f32_e32 v81, v81
	v_exp_f32_e32 v83, v83
	v_add_f32_e32 v82, v86, v87
	v_add_f32_e32 v86, v90, v82
	v_cvt_pk_bf16_f32 v82, v80, v81
	v_cvt_pk_bf16_f32 v83, v91, v83
	v_lshlrev_b32_e32 v80, 16, v82
	v_and_b32_e32 v81, 0xffff0000, v82
	v_lshlrev_b32_e32 v87, 16, v83
	v_and_b32_e32 v90, 0xffff0000, v83
	v_add_f32_e32 v80, v80, v81
	v_add_f32_e32 v81, v87, v90
	v_add_f32_e32 v80, v80, v81
	v_add_f32_e32 v90, v86, v80
	ds_bpermute_b32 v91, v151, v90
	v_lshl_add_u64 v[80:81], s[46:47], 0, v[92:93]
	v_lshl_add_u64 v[80:81], s[74:75], 1, v[80:81]
	v_lshl_add_u64 v[80:81], v[80:81], 0, s[54:55]
	v_lshl_add_u64 v[86:87], v[80:81], 0, v[132:133]
	s_waitcnt lgkmcnt(0)
	v_add_f32_e32 v80, v90, v91
	ds_bpermute_b32 v81, v150, v80
	v_mov_b32_e32 v200, v94
	v_mov_b32_e32 v201, v95
	v_mov_b32_e32 v202, v88
	v_mov_b32_e32 v203, v89
	v_mov_b32_e32 v204, v84
	v_mov_b32_e32 v205, v85
	v_mov_b32_e32 v206, v82
	v_mov_b32_e32 v207, v83
	v_permlane32_swap_b32_e32 v200, v202
	v_permlane32_swap_b32_e32 v201, v203
	v_permlane32_swap_b32_e32 v204, v206
	v_permlane32_swap_b32_e32 v205, v207
	v_permlane16_swap_b32_e32 v200, v202
	v_permlane16_swap_b32_e32 v201, v203
	v_permlane16_swap_b32_e32 v204, v206
	v_permlane16_swap_b32_e32 v205, v207
	v_lshl_add_u64 v[208:209], v[86:87], 0, v[250:251]
	global_store_dwordx4 v[208:209], v[200:203], off
	global_store_dwordx4 v[208:209], v[204:207], off offset:256
	s_and_saveexec_b64 s[28:29], s[6:7]
	s_cbranch_execz .LBB0_371
	s_waitcnt lgkmcnt(0)
	v_add_f32_e32 v82, v80, v81
	v_lshlrev_b32_e32 v80, 2, v96
	v_ashrrev_i32_e32 v81, 31, v80
	v_lshl_add_u64 v[80:81], v[80:81], 2, s[44:45]
	s_ashr_i32 s31, s30, 31
	v_lshl_add_u64 v[80:81], s[30:31], 2, v[80:81]
	global_atomic_add_f32 v[80:81], v82, off
.LBB0_371:
	s_or_b64 exec, exec, s[28:29]
	v_exp_f32_e32 v82, v76
	v_exp_f32_e32 v83, v77
	v_exp_f32_e32 v84, v78
	v_exp_f32_e32 v79, v79
	v_exp_f32_e32 v72, v72
	v_exp_f32_e32 v73, v73
	v_exp_f32_e32 v74, v74
	v_exp_f32_e32 v75, v75
	v_add_u32_e32 v80, s67, v137
	s_waitcnt lgkmcnt(0)
	v_ashrrev_i32_e32 v81, 31, v80
	v_cvt_pk_bf16_f32 v78, v82, v83
	v_cvt_pk_bf16_f32 v79, v84, v79
	v_lshlrev_b64 v[76:77], 11, v[80:81]
	v_lshlrev_b32_e32 v81, 16, v78
	v_and_b32_e32 v82, 0xffff0000, v78
	v_lshlrev_b32_e32 v83, 16, v79
	v_and_b32_e32 v84, 0xffff0000, v79
	v_exp_f32_e32 v68, v68
	v_exp_f32_e32 v69, v69
	v_exp_f32_e32 v70, v70
	v_exp_f32_e32 v71, v71
	v_add_f32_e32 v81, v81, v82
	v_add_f32_e32 v82, v83, v84
	v_cvt_pk_bf16_f32 v72, v72, v73
	v_cvt_pk_bf16_f32 v73, v74, v75
	v_add_f32_e32 v81, v81, v82
	v_lshlrev_b32_e32 v74, 16, v72
	v_and_b32_e32 v75, 0xffff0000, v72
	v_lshlrev_b32_e32 v82, 16, v73
	v_and_b32_e32 v83, 0xffff0000, v73
	v_add_f32_e32 v74, v74, v75
	v_add_f32_e32 v75, v82, v83
	v_add_f32_e32 v81, 0, v81
	v_add_f32_e32 v74, v74, v75
	v_cvt_pk_bf16_f32 v68, v68, v69
	v_cvt_pk_bf16_f32 v69, v70, v71
	v_add_f32_e32 v74, v81, v74
	v_lshlrev_b32_e32 v70, 16, v68
	v_and_b32_e32 v71, 0xffff0000, v68
	v_lshlrev_b32_e32 v75, 16, v69
	v_and_b32_e32 v81, 0xffff0000, v69
	v_add_f32_e32 v70, v70, v71
	v_add_f32_e32 v71, v75, v81
	v_exp_f32_e32 v75, v66
	v_exp_f32_e32 v64, v64
	v_exp_f32_e32 v65, v65
	v_exp_f32_e32 v67, v67
	v_add_f32_e32 v66, v70, v71
	v_add_f32_e32 v70, v74, v66
	v_cvt_pk_bf16_f32 v66, v64, v65
	v_cvt_pk_bf16_f32 v67, v75, v67
	v_lshlrev_b32_e32 v64, 16, v66
	v_and_b32_e32 v65, 0xffff0000, v66
	v_lshlrev_b32_e32 v71, 16, v67
	v_and_b32_e32 v74, 0xffff0000, v67
	v_add_f32_e32 v64, v64, v65
	v_add_f32_e32 v65, v71, v74
	v_add_f32_e32 v64, v64, v65
	v_add_f32_e32 v74, v70, v64
	ds_bpermute_b32 v75, v151, v74
	v_lshl_add_u64 v[64:65], s[46:47], 0, v[76:77]
	v_lshl_add_u64 v[64:65], s[74:75], 1, v[64:65]
	v_lshl_add_u64 v[64:65], v[64:65], 0, s[54:55]
	v_lshl_add_u64 v[70:71], v[64:65], 0, v[132:133]
	s_waitcnt lgkmcnt(0)
	v_add_f32_e32 v64, v74, v75
	ds_bpermute_b32 v65, v150, v64
	v_mov_b32_e32 v212, v78
	v_mov_b32_e32 v213, v79
	v_mov_b32_e32 v214, v72
	v_mov_b32_e32 v215, v73
	v_mov_b32_e32 v216, v68
	v_mov_b32_e32 v217, v69
	v_mov_b32_e32 v218, v66
	v_mov_b32_e32 v219, v67
	v_permlane32_swap_b32_e32 v212, v214
	v_permlane32_swap_b32_e32 v213, v215
	v_permlane32_swap_b32_e32 v216, v218
	v_permlane32_swap_b32_e32 v217, v219
	v_permlane16_swap_b32_e32 v212, v214
	v_permlane16_swap_b32_e32 v213, v215
	v_permlane16_swap_b32_e32 v216, v218
	v_permlane16_swap_b32_e32 v217, v219
	v_lshl_add_u64 v[208:209], v[70:71], 0, v[250:251]
	global_store_dwordx4 v[208:209], v[212:215], off
	global_store_dwordx4 v[208:209], v[216:219], off offset:256
	s_and_saveexec_b64 s[28:29], s[6:7]
	s_cbranch_execz .LBB0_373
	s_waitcnt lgkmcnt(0)
	v_add_f32_e32 v66, v64, v65
	v_lshlrev_b32_e32 v64, 2, v80
	v_ashrrev_i32_e32 v65, 31, v64
	v_lshl_add_u64 v[64:65], v[64:65], 2, s[44:45]
	s_ashr_i32 s31, s30, 31
	v_lshl_add_u64 v[64:65], s[30:31], 2, v[64:65]
	global_atomic_add_f32 v[64:65], v66, off
; __device__ __forceinline__ u32x2 pk4(f32x4 v) { u32x2 r; r.x = pk_bf16(v[0], v[1]); r.y = pk_bf16(v[2], v[3]); return r; }
; __device__ __forceinline__ f32x4 unpk4(u32x2 v) { return (f32x4){bf_lo(v.x), bf_hi(v.x), bf_lo(v.y), bf_hi(v.y)}; }
;     __device__ __forceinline__ void operator()(const f32x4 (&acc)[2][2][4][2], const Unit& u, int wr, int wc, int fr, int fq) const {
; #pragma unroll
;         for (int ai = 0; ai < 2; ++ai)
; #pragma unroll
;             for (int m = 0; m < 4; ++m) {
;                 const int row = u.pm * 256 + ai * 128 + wr * 64 + m * 16 + fr; float rs = 0.f;
; #pragma unroll
;                 for (int bj = 0; bj < 2; ++bj)
; #pragma unroll
;                     for (int n = 0; n < 2; ++n) {
;                         const f32x4 s = acc[ai][bj][m][n]; f32x4 e;
; #pragma unroll
;                         for (int j = 0; j < 4; ++j) e[j] = __builtin_amdgcn_exp2f(1.44269504089f * s[j]);
;                         const u32x2 w = pk4(e); const f32x4 er = unpk4(w); rs += (er[0] + er[1]) + (er[2] + er[3]);
;                         *(u32x2*)(Q + (size_t)row * 1024 + u.pn * 256 + bj * 128 + wc * 32 + n * 16 + fq * 4) = w;
;                     }
;                 rs += __shfl_xor(rs, 16); rs += __shfl_xor(rs, 32);
;                 if (fq == 0) unsafeAtomicAdd(RSUM + row * 4 + u.pn, rs);
;             }
.LBB0_373:
	s_or_b64 exec, exec, s[28:29]
	v_exp_f32_e32 v66, v60
	v_exp_f32_e32 v67, v61
	v_exp_f32_e32 v68, v62
	v_exp_f32_e32 v63, v63
	v_exp_f32_e32 v56, v56
	v_exp_f32_e32 v57, v57
	v_exp_f32_e32 v58, v58
	v_exp_f32_e32 v59, v59
	v_add_u32_e32 v64, s67, v140
	s_waitcnt lgkmcnt(0)
	v_ashrrev_i32_e32 v65, 31, v64
	v_cvt_pk_bf16_f32 v62, v66, v67
	v_cvt_pk_bf16_f32 v63, v68, v63
	v_lshlrev_b64 v[60:61], 11, v[64:65]
	v_lshlrev_b32_e32 v65, 16, v62
	v_and_b32_e32 v66, 0xffff0000, v62
	v_lshlrev_b32_e32 v67, 16, v63
	v_and_b32_e32 v68, 0xffff0000, v63
	v_exp_f32_e32 v52, v52
	v_exp_f32_e32 v53, v53
	v_exp_f32_e32 v54, v54
	v_exp_f32_e32 v55, v55
	v_add_f32_e32 v65, v65, v66
	v_add_f32_e32 v66, v67, v68
	v_cvt_pk_bf16_f32 v56, v56, v57
	v_cvt_pk_bf16_f32 v57, v58, v59
	v_add_f32_e32 v65, v65, v66
	v_lshlrev_b32_e32 v58, 16, v56
	v_and_b32_e32 v59, 0xffff0000, v56
	v_lshlrev_b32_e32 v66, 16, v57
	v_and_b32_e32 v67, 0xffff0000, v57
	v_add_f32_e32 v58, v58, v59
	v_add_f32_e32 v59, v66, v67
	v_add_f32_e32 v65, 0, v65
	v_add_f32_e32 v58, v58, v59
	v_cvt_pk_bf16_f32 v52, v52, v53
	v_cvt_pk_bf16_f32 v53, v54, v55
	v_add_f32_e32 v58, v65, v58
	v_lshlrev_b32_e32 v54, 16, v52
	v_and_b32_e32 v55, 0xffff0000, v52
	v_lshlrev_b32_e32 v59, 16, v53
	v_and_b32_e32 v65, 0xffff0000, v53
	v_add_f32_e32 v54, v54, v55
	v_add_f32_e32 v55, v59, v65
	v_exp_f32_e32 v59, v50
	v_exp_f32_e32 v48, v48
	v_exp_f32_e32 v49, v49
	v_exp_f32_e32 v51, v51
	v_add_f32_e32 v50, v54, v55
	v_add_f32_e32 v54, v58, v50
	v_cvt_pk_bf16_f32 v50, v48, v49
	v_cvt_pk_bf16_f32 v51, v59, v51
	v_lshlrev_b32_e32 v48, 16, v50
	v_and_b32_e32 v49, 0xffff0000, v50
	v_lshlrev_b32_e32 v55, 16, v51
	v_and_b32_e32 v58, 0xffff0000, v51
	v_add_f32_e32 v48, v48, v49
	v_add_f32_e32 v49, v55, v58
	v_add_f32_e32 v48, v48, v49
	v_add_f32_e32 v58, v54, v48
	ds_bpermute_b32 v59, v151, v58
	v_lshl_add_u64 v[48:49], s[46:47], 0, v[60:61]
	v_lshl_add_u64 v[48:49], s[74:75], 1, v[48:49]
	v_lshl_add_u64 v[48:49], v[48:49], 0, s[54:55]
	v_lshl_add_u64 v[54:55], v[48:49], 0, v[132:133]
	s_waitcnt lgkmcnt(0)
	v_add_f32_e32 v48, v58, v59
	ds_bpermute_b32 v49, v150, v48
	v_mov_b32_e32 v200, v62
	v_mov_b32_e32 v201, v63
	v_mov_b32_e32 v202, v56
	v_mov_b32_e32 v203, v57
	v_mov_b32_e32 v204, v52
	v_mov_b32_e32 v205, v53
	v_mov_b32_e32 v206, v50
	v_mov_b32_e32 v207, v51
	v_permlane32_swap_b32_e32 v200, v202
	v_permlane32_swap_b32_e32 v201, v203
	v_permlane32_swap_b32_e32 v204, v206
	v_permlane32_swap_b32_e32 v205, v207
	v_permlane16_swap_b32_e32 v200, v202
	v_permlane16_swap_b32_e32 v201, v203
	v_permlane16_swap_b32_e32 v204, v206
	v_permlane16_swap_b32_e32 v205, v207
	v_lshl_add_u64 v[208:209], v[54:55], 0, v[250:251]
	global_store_dwordx4 v[208:209], v[200:203], off
	global_store_dwordx4 v[208:209], v[204:207], off offset:256
	s_and_saveexec_b64 s[28:29], s[6:7]
	s_cbranch_execz .LBB0_375
	s_waitcnt lgkmcnt(0)
	v_add_f32_e32 v50, v48, v49
	v_lshlrev_b32_e32 v48, 2, v64
	v_ashrrev_i32_e32 v49, 31, v48
	v_lshl_add_u64 v[48:49], v[48:49], 2, s[44:45]
	s_ashr_i32 s31, s30, 31
	v_lshl_add_u64 v[48:49], s[30:31], 2, v[48:49]
	global_atomic_add_f32 v[48:49], v50, off
.LBB0_375:
	s_or_b64 exec, exec, s[28:29]
	v_exp_f32_e32 v50, v44
	v_exp_f32_e32 v51, v45
	v_exp_f32_e32 v52, v46
	v_exp_f32_e32 v47, v47
	v_exp_f32_e32 v40, v40
	v_exp_f32_e32 v41, v41
	v_exp_f32_e32 v42, v42
	v_exp_f32_e32 v43, v43
	v_add_u32_e32 v48, s67, v141
	s_waitcnt lgkmcnt(0)
	v_ashrrev_i32_e32 v49, 31, v48
	v_cvt_pk_bf16_f32 v46, v50, v51
	v_cvt_pk_bf16_f32 v47, v52, v47
	v_lshlrev_b64 v[44:45], 11, v[48:49]
	v_lshlrev_b32_e32 v49, 16, v46
	v_and_b32_e32 v50, 0xffff0000, v46
	v_lshlrev_b32_e32 v51, 16, v47
	v_and_b32_e32 v52, 0xffff0000, v47
	v_exp_f32_e32 v36, v36
	v_exp_f32_e32 v37, v37
	v_exp_f32_e32 v38, v38
	v_exp_f32_e32 v39, v39
	v_add_f32_e32 v49, v49, v50
	v_add_f32_e32 v50, v51, v52
	v_cvt_pk_bf16_f32 v40, v40, v41
	v_cvt_pk_bf16_f32 v41, v42, v43
	v_add_f32_e32 v49, v49, v50
	v_lshlrev_b32_e32 v42, 16, v40
	v_and_b32_e32 v43, 0xffff0000, v40
	v_lshlrev_b32_e32 v50, 16, v41
	v_and_b32_e32 v51, 0xffff0000, v41
	v_add_f32_e32 v42, v42, v43
	v_add_f32_e32 v43, v50, v51
	v_add_f32_e32 v49, 0, v49
	v_add_f32_e32 v42, v42, v43
	v_cvt_pk_bf16_f32 v36, v36, v37
	v_cvt_pk_bf16_f32 v37, v38, v39
	v_add_f32_e32 v42, v49, v42
	v_lshlrev_b32_e32 v38, 16, v36
	v_and_b32_e32 v39, 0xffff0000, v36
	v_lshlrev_b32_e32 v43, 16, v37
	v_and_b32_e32 v49, 0xffff0000, v37
	v_add_f32_e32 v38, v38, v39
	v_add_f32_e32 v39, v43, v49
	v_exp_f32_e32 v43, v34
	v_exp_f32_e32 v32, v32
	v_exp_f32_e32 v33, v33
	v_exp_f32_e32 v35, v35
	v_add_f32_e32 v34, v38, v39
	v_add_f32_e32 v38, v42, v34
	v_cvt_pk_bf16_f32 v34, v32, v33
	v_cvt_pk_bf16_f32 v35, v43, v35
	v_lshlrev_b32_e32 v32, 16, v34
	v_and_b32_e32 v33, 0xffff0000, v34
	v_lshlrev_b32_e32 v39, 16, v35
	v_and_b32_e32 v42, 0xffff0000, v35
	v_add_f32_e32 v32, v32, v33
	v_add_f32_e32 v33, v39, v42
	v_add_f32_e32 v32, v32, v33
	v_add_f32_e32 v42, v38, v32
	ds_bpermute_b32 v43, v151, v42
	v_lshl_add_u64 v[32:33], s[46:47], 0, v[44:45]
	v_lshl_add_u64 v[32:33], s[74:75], 1, v[32:33]
	v_lshl_add_u64 v[32:33], v[32:33], 0, s[54:55]
	v_lshl_add_u64 v[38:39], v[32:33], 0, v[132:133]
	s_waitcnt lgkmcnt(0)
	v_add_f32_e32 v32, v42, v43
	ds_bpermute_b32 v33, v150, v32
	v_mov_b32_e32 v212, v46
	v_mov_b32_e32 v213, v47
	v_mov_b32_e32 v214, v40
	v_mov_b32_e32 v215, v41
	v_mov_b32_e32 v216, v36
	v_mov_b32_e32 v217, v37
	v_mov_b32_e32 v218, v34
	v_mov_b32_e32 v219, v35
	v_permlane32_swap_b32_e32 v212, v214
	v_permlane32_swap_b32_e32 v213, v215
	v_permlane32_swap_b32_e32 v216, v218
	v_permlane32_swap_b32_e32 v217, v219
	v_permlane16_swap_b32_e32 v212, v214
	v_permlane16_swap_b32_e32 v213, v215
	v_permlane16_swap_b32_e32 v216, v218
	v_permlane16_swap_b32_e32 v217, v219
	v_lshl_add_u64 v[208:209], v[38:39], 0, v[250:251]
	global_store_dwordx4 v[208:209], v[212:215], off
	global_store_dwordx4 v[208:209], v[216:219], off offset:256
	s_and_saveexec_b64 s[28:29], s[6:7]
	s_cbranch_execz .LBB0_377
	s_waitcnt lgkmcnt(0)
	v_add_f32_e32 v34, v32, v33
	v_lshlrev_b32_e32 v32, 2, v48
	v_ashrrev_i32_e32 v33, 31, v32
	v_lshl_add_u64 v[32:33], v[32:33], 2, s[44:45]
	s_ashr_i32 s31, s30, 31
	v_lshl_add_u64 v[32:33], s[30:31], 2, v[32:33]
	global_atomic_add_f32 v[32:33], v34, off
; __device__ __forceinline__ u32x2 pk4(f32x4 v) { u32x2 r; r.x = pk_bf16(v[0], v[1]); r.y = pk_bf16(v[2], v[3]); return r; }
; __device__ __forceinline__ f32x4 unpk4(u32x2 v) { return (f32x4){bf_lo(v.x), bf_hi(v.x), bf_lo(v.y), bf_hi(v.y)}; }
;     __device__ __forceinline__ void operator()(const f32x4 (&acc)[2][2][4][2], const Unit& u, int wr, int wc, int fr, int fq) const {
; #pragma unroll
;         for (int ai = 0; ai < 2; ++ai)
; #pragma unroll
;             for (int m = 0; m < 4; ++m) {
;                 const int row = u.pm * 256 + ai * 128 + wr * 64 + m * 16 + fr; float rs = 0.f;
; #pragma unroll
;                 for (int bj = 0; bj < 2; ++bj)
; #pragma unroll
;                     for (int n = 0; n < 2; ++n) {
;                         const f32x4 s = acc[ai][bj][m][n]; f32x4 e;
; #pragma unroll
;                         for (int j = 0; j < 4; ++j) e[j] = __builtin_amdgcn_exp2f(1.44269504089f * s[j]);
;                         const u32x2 w = pk4(e); const f32x4 er = unpk4(w); rs += (er[0] + er[1]) + (er[2] + er[3]);
;                         *(u32x2*)(Q + (size_t)row * 1024 + u.pn * 256 + bj * 128 + wc * 32 + n * 16 + fq * 4) = w;
;                     }
;                 rs += __shfl_xor(rs, 16); rs += __shfl_xor(rs, 32);
;                 if (fq == 0) unsafeAtomicAdd(RSUM + row * 4 + u.pn, rs);
;             }
.LBB0_377:
	s_or_b64 exec, exec, s[28:29]
	v_exp_f32_e32 v34, v28
	v_exp_f32_e32 v35, v29
	v_exp_f32_e32 v36, v30
	v_exp_f32_e32 v31, v31
	v_exp_f32_e32 v24, v24
	v_exp_f32_e32 v25, v25
	v_exp_f32_e32 v26, v26
	v_exp_f32_e32 v27, v27
	v_add_u32_e32 v32, s67, v142
	s_waitcnt lgkmcnt(0)
	v_ashrrev_i32_e32 v33, 31, v32
	v_cvt_pk_bf16_f32 v30, v34, v35
	v_cvt_pk_bf16_f32 v31, v36, v31
	v_lshlrev_b64 v[28:29], 11, v[32:33]
	v_lshlrev_b32_e32 v33, 16, v30
	v_and_b32_e32 v34, 0xffff0000, v30
	v_lshlrev_b32_e32 v35, 16, v31
	v_and_b32_e32 v36, 0xffff0000, v31
	v_exp_f32_e32 v20, v20
	v_exp_f32_e32 v21, v21
	v_exp_f32_e32 v22, v22
	v_exp_f32_e32 v23, v23
	v_add_f32_e32 v33, v33, v34
	v_add_f32_e32 v34, v35, v36
	v_cvt_pk_bf16_f32 v24, v24, v25
	v_cvt_pk_bf16_f32 v25, v26, v27
	v_add_f32_e32 v33, v33, v34
	v_lshlrev_b32_e32 v26, 16, v24
	v_and_b32_e32 v27, 0xffff0000, v24
	v_lshlrev_b32_e32 v34, 16, v25
	v_and_b32_e32 v35, 0xffff0000, v25
	v_add_f32_e32 v26, v26, v27
	v_add_f32_e32 v27, v34, v35
	v_add_f32_e32 v33, 0, v33
	v_add_f32_e32 v26, v26, v27
	v_cvt_pk_bf16_f32 v20, v20, v21
	v_cvt_pk_bf16_f32 v21, v22, v23
	v_add_f32_e32 v26, v33, v26
	v_lshlrev_b32_e32 v22, 16, v20
	v_and_b32_e32 v23, 0xffff0000, v20
	v_lshlrev_b32_e32 v27, 16, v21
	v_and_b32_e32 v33, 0xffff0000, v21
	v_add_f32_e32 v22, v22, v23
	v_add_f32_e32 v23, v27, v33
	v_exp_f32_e32 v27, v18
	v_exp_f32_e32 v16, v16
	v_exp_f32_e32 v17, v17
	v_exp_f32_e32 v19, v19
	v_add_f32_e32 v18, v22, v23
	v_add_f32_e32 v22, v26, v18
	v_cvt_pk_bf16_f32 v18, v16, v17
	v_cvt_pk_bf16_f32 v19, v27, v19
	v_lshlrev_b32_e32 v16, 16, v18
	v_and_b32_e32 v17, 0xffff0000, v18
	v_lshlrev_b32_e32 v23, 16, v19
	v_and_b32_e32 v26, 0xffff0000, v19
	v_add_f32_e32 v16, v16, v17
	v_add_f32_e32 v17, v23, v26
	v_add_f32_e32 v16, v16, v17
	v_add_f32_e32 v26, v22, v16
	ds_bpermute_b32 v27, v151, v26
	v_lshl_add_u64 v[16:17], s[46:47], 0, v[28:29]
	v_lshl_add_u64 v[16:17], s[74:75], 1, v[16:17]
	v_lshl_add_u64 v[16:17], v[16:17], 0, s[54:55]
	v_lshl_add_u64 v[22:23], v[16:17], 0, v[132:133]
	s_waitcnt lgkmcnt(0)
	v_add_f32_e32 v16, v26, v27
	ds_bpermute_b32 v17, v150, v16
	v_mov_b32_e32 v200, v30
	v_mov_b32_e32 v201, v31
	v_mov_b32_e32 v202, v24
	v_mov_b32_e32 v203, v25
	v_mov_b32_e32 v204, v20
	v_mov_b32_e32 v205, v21
	v_mov_b32_e32 v206, v18
	v_mov_b32_e32 v207, v19
	v_permlane32_swap_b32_e32 v200, v202
	v_permlane32_swap_b32_e32 v201, v203
	v_permlane32_swap_b32_e32 v204, v206
	v_permlane32_swap_b32_e32 v205, v207
	v_permlane16_swap_b32_e32 v200, v202
	v_permlane16_swap_b32_e32 v201, v203
	v_permlane16_swap_b32_e32 v204, v206
	v_permlane16_swap_b32_e32 v205, v207
	v_lshl_add_u64 v[208:209], v[22:23], 0, v[250:251]
	global_store_dwordx4 v[208:209], v[200:203], off
	global_store_dwordx4 v[208:209], v[204:207], off offset:256
	s_and_saveexec_b64 s[28:29], s[6:7]
	s_cbranch_execz .LBB0_379
	s_waitcnt lgkmcnt(0)
	v_add_f32_e32 v18, v16, v17
	v_lshlrev_b32_e32 v16, 2, v32
	v_ashrrev_i32_e32 v17, 31, v16
	v_lshl_add_u64 v[16:17], v[16:17], 2, s[44:45]
	s_ashr_i32 s31, s30, 31
	v_lshl_add_u64 v[16:17], s[30:31], 2, v[16:17]
	global_atomic_add_f32 v[16:17], v18, off
.LBB0_379:
	s_or_b64 exec, exec, s[28:29]
	v_exp_f32_e32 v18, v12
	v_exp_f32_e32 v19, v13
	v_exp_f32_e32 v20, v14
	v_exp_f32_e32 v15, v15
	v_exp_f32_e32 v8, v8
	v_exp_f32_e32 v9, v9
	v_exp_f32_e32 v10, v10
	v_exp_f32_e32 v11, v11
	v_add_u32_e32 v16, s67, v143
	s_waitcnt lgkmcnt(0)
	v_ashrrev_i32_e32 v17, 31, v16
	v_cvt_pk_bf16_f32 v14, v18, v19
	v_cvt_pk_bf16_f32 v15, v20, v15
	v_lshlrev_b64 v[12:13], 11, v[16:17]
	v_lshlrev_b32_e32 v17, 16, v14
	v_and_b32_e32 v18, 0xffff0000, v14
	v_lshlrev_b32_e32 v19, 16, v15
	v_and_b32_e32 v20, 0xffff0000, v15
	v_exp_f32_e32 v4, v4
	v_exp_f32_e32 v5, v5
	v_exp_f32_e32 v6, v6
	v_exp_f32_e32 v7, v7
	v_add_f32_e32 v17, v17, v18
	v_add_f32_e32 v18, v19, v20
	v_cvt_pk_bf16_f32 v8, v8, v9
	v_cvt_pk_bf16_f32 v9, v10, v11
	v_add_f32_e32 v17, v17, v18
	v_lshlrev_b32_e32 v10, 16, v8
	v_and_b32_e32 v11, 0xffff0000, v8
	v_lshlrev_b32_e32 v18, 16, v9
	v_and_b32_e32 v19, 0xffff0000, v9
	v_add_f32_e32 v10, v10, v11
	v_add_f32_e32 v11, v18, v19
	v_add_f32_e32 v17, 0, v17
	v_add_f32_e32 v10, v10, v11
	v_cvt_pk_bf16_f32 v4, v4, v5
	v_cvt_pk_bf16_f32 v5, v6, v7
	v_add_f32_e32 v10, v17, v10
	v_lshlrev_b32_e32 v6, 16, v4
	v_and_b32_e32 v7, 0xffff0000, v4
	v_lshlrev_b32_e32 v11, 16, v5
	v_and_b32_e32 v17, 0xffff0000, v5
	v_add_f32_e32 v6, v6, v7
	v_add_f32_e32 v7, v11, v17
	v_exp_f32_e32 v11, v2
	v_exp_f32_e32 v0, v0
	v_exp_f32_e32 v1, v1
	v_exp_f32_e32 v3, v3
	v_add_f32_e32 v2, v6, v7
	v_add_f32_e32 v6, v10, v2
	v_cvt_pk_bf16_f32 v2, v0, v1
	v_cvt_pk_bf16_f32 v3, v11, v3
	v_lshlrev_b32_e32 v0, 16, v2
	v_and_b32_e32 v1, 0xffff0000, v2
	v_lshlrev_b32_e32 v7, 16, v3
	v_and_b32_e32 v10, 0xffff0000, v3
	v_add_f32_e32 v0, v0, v1
	v_add_f32_e32 v1, v7, v10
	v_add_f32_e32 v0, v0, v1
	v_add_f32_e32 v10, v6, v0
	ds_bpermute_b32 v11, v151, v10
	v_lshl_add_u64 v[0:1], s[46:47], 0, v[12:13]
	v_lshl_add_u64 v[0:1], s[74:75], 1, v[0:1]
	v_lshl_add_u64 v[0:1], v[0:1], 0, s[54:55]
	v_lshl_add_u64 v[6:7], v[0:1], 0, v[132:133]
	s_waitcnt lgkmcnt(0)
	v_add_f32_e32 v0, v10, v11
	ds_bpermute_b32 v1, v150, v0
	v_mov_b32_e32 v212, v14
	v_mov_b32_e32 v213, v15
	v_mov_b32_e32 v214, v8
	v_mov_b32_e32 v215, v9
	v_mov_b32_e32 v216, v4
	v_mov_b32_e32 v217, v5
	v_mov_b32_e32 v218, v2
	v_mov_b32_e32 v219, v3
	v_permlane32_swap_b32_e32 v212, v214
	v_permlane32_swap_b32_e32 v213, v215
	v_permlane32_swap_b32_e32 v216, v218
	v_permlane32_swap_b32_e32 v217, v219
	v_permlane16_swap_b32_e32 v212, v214
	v_permlane16_swap_b32_e32 v213, v215
	v_permlane16_swap_b32_e32 v216, v218
	v_permlane16_swap_b32_e32 v217, v219
	v_lshl_add_u64 v[208:209], v[6:7], 0, v[250:251]
	global_store_dwordx4 v[208:209], v[212:215], off
	global_store_dwordx4 v[208:209], v[216:219], off offset:256
	s_and_saveexec_b64 s[28:29], s[6:7]
	s_cbranch_execz .LBB0_381
	s_waitcnt lgkmcnt(0)
	v_add_f32_e32 v2, v0, v1
	v_lshlrev_b32_e32 v0, 2, v16
	v_ashrrev_i32_e32 v1, 31, v0
	v_lshl_add_u64 v[0:1], v[0:1], 2, s[44:45]
	s_ashr_i32 s31, s30, 31
	v_lshl_add_u64 v[0:1], s[30:31], 2, v[0:1]
	global_atomic_add_f32 v[0:1], v2, off
